# attention loops: one static s_setprio 1 for waves 4-7 (second wave of each SIMD) at loop entry, reset at loop exit; bit-identical
# baseline (speedup 1.0000x reference)
; DEV int ltid() { int t = threadIdx.x; asm volatile("" : "+v"(t)); return t; }
; DEV int v_st(int k, int c) { const int kk = (k & ~0xC) | ((k & 4) << 1) | ((k & 8) >> 1); return ((kk >> 3) * 4 + (c >> 5)) * 512 + ((kk & 7) * 32 + (c & 31)) * 2; }
; DEV int v_rd_base(int lane) { return ((lane & 3) << 3) | (((lane >> 2) & 3) << 6) | (((lane >> 4) & 1) << 5) | (((lane >> 5) & 1) << 8); }
; #define SLOAD(i, k0) do { sr_[i].vs0 = *reinterpret_cast<const bf16x8*>(&Vh[(size_t)((k0) + sr) * 128 + sc]); sr_[i].vs1 = *reinterpret_cast<const bf16x8*>(&Vh[(size_t)((k0) + 32 + sr) * 128 + sc]); \
;     sr_[i].ks0 = *reinterpret_cast<const bf16x8*>(&Kh[(size_t)((k0) + kr) * 64 + kc]); } while (0)
; #define SWRITE(b, i) do { *(bf16x8*)(V_lds + (b) * AT_SHM_V + vst0) = sr_[i].vs0; *(bf16x8*)(V_lds + (b) * AT_SHM_V + vst1) = sr_[i].vs1; \
;     *(bf16x8*)(K_lds + (b) * AT_SHM_K + kst) = sr_[i].ks0; } while (0)
; DEV void attn_pass(const u16* __restrict__ Qb, const u16* __restrict__ Kh, const u16* __restrict__ Vh, int seq, f32x16* o, float* rli) {
;   char* lds = g_shm;
;   const int tid = ltid(), wid = tid >> 6, lane = tid & 63, r32 = lane & 31, hi = lane >> 5;
;   char* V_lds = lds; char* K_lds = lds + 3 * AT_SHM_V;
;   float* wsx = (float*)(lds + 3 * AT_SHM_V + 3 * AT_SHM_K) + wid * 64; float* li_l = wsx; float* al_l = wsx + 32;
;   float m_reg = -1e30f, l_reg = 0; bf16x8 qr[4];
; #pragma unroll
;   for (int d = 0; d < 4; ++d) o[d] = f32x16{};
;   const u16* Qw = Qb + (size_t)(wid * 32 + r32) * 64 + hi * 8;
; #pragma unroll
;   for (int d0 = 0; d0 < 4; ++d0) qr[d0] = *reinterpret_cast<const bf16x8*>(Qw + d0 * 16);
;   const int sr = tid >> 4, sc = (tid & 15) * 8, vst0 = v_st(sr, sc), vst1 = v_st(32 + sr, sc);
;   const int kr = tid >> 3, kc = (tid & 7) * 8, kst = KSWZ64(kr, kc * 2);
;   const int vb0 = (int)(uintptr_t)(__attribute__((address_space(3))) char*)V_lds + v_rd_base(lane);
;   struct { bf16x8 vs0, vs1, ks0; } sr_[2];
;     ...
;   f32x16 pA0, pA1, pB0, pB1; float mnA, mnB, alA, alB; bf16x8 pa0, pa1, pa2, pa3; const int NT = seq / 64;
;   constexpr int SE = 0, SO = 1;
;   SLOAD(SE, 0); SLOAD(SO, 64);
;   asm volatile("s_waitcnt vmcnt(3)" ::: "memory"); SWRITE(0, SE); __syncthreads();
;   if (2 < NT) SLOAD(SE, 2 * 64);
;   qkt(pA0, pA1, K_lds, qr, r32, hi); partialSM(pA0, pA1, m_reg, mnA, alA);
.LBB0_69:
	s_and_b32 s43, s10, 7
	s_addk_i32 s11, 0x100
	s_and_b64 s[6:7], s[6:7], exec
	s_cselect_b32 s44, 4, 0x44
	s_cselect_b32 s46, 0, s11
	s_lshl_b32 s1, s0, 3
	s_or_b32 s49, s1, s43
	s_mul_i32 s52, s49, 0x110000
	s_mul_hi_i32 s53, s49, 0x110000
	s_add_u32 s64, s40, s52
	s_addc_u32 s65, s41, s53
	s_lshl_b32 s0, s0, 4
	s_lshl_b32 s1, s43, 1
	s_or_b32 s47, s0, s1
	s_mul_i32 s0, s47, 0x1100
	s_mul_hi_i32 s1, s47, 0x1100
	s_add_u32 s0, s0, s46
	v_mov_b32_e32 v70, v252
	s_addc_u32 s1, s1, 0
	s_lshl_b64 s[0:1], s[0:1], 7
	v_ashrrev_i32_e32 v48, 4, v70
	v_lshlrev_b32_e32 v20, 3, v70
	v_ashrrev_i32_e32 v49, 31, v48
	s_add_u32 s0, s36, s0
	v_and_b32_e32 v2, 0x78, v20
	v_add_u32_e32 v12, 32, v48
	v_lshlrev_b64 v[50:51], 8, v[48:49]
	s_addc_u32 s1, s37, s1
	s_mul_i32 s62, s47, 0x88000
	v_ashrrev_i32_e32 v14, 3, v70
	v_lshl_add_u64 v[0:1], s[64:65], 0, v[50:51]
	v_lshlrev_b32_e32 v2, 1, v2
	v_mov_b32_e32 v3, v163
	v_ashrrev_i32_e32 v13, 31, v12
	s_mul_hi_i32 s63, s47, 0x88000
	s_add_u32 s6, s38, s62
	v_lshl_add_u64 v[66:67], v[0:1], 0, v[2:3]
	v_lshlrev_b64 v[0:1], 8, v[12:13]
	v_ashrrev_i32_e32 v15, 31, v14
	s_addc_u32 s7, s39, s63
	v_lshlrev_b32_e32 v71, 4, v70
	v_lshl_add_u64 v[0:1], s[64:65], 0, v[0:1]
	v_lshlrev_b64 v[52:53], 7, v[14:15]
	v_and_b32_e32 v16, 0x70, v71
	v_lshl_add_u64 v[4:5], v[0:1], 0, v[2:3]
	v_lshl_add_u64 v[8:9], s[6:7], 0, v[52:53]
	v_mov_b32_e32 v17, v163
	global_load_dwordx4 v[0:3], v[66:67], off
	s_nop 0
	global_load_dwordx4 v[4:7], v[4:5], off
	v_lshl_add_u64 v[68:69], v[8:9], 0, v[16:17]
	global_load_dwordx4 v[8:11], v[68:69], off
	v_ashrrev_i32_e32 v13, 1, v70
	v_bfi_b32 v18, s68, v13, v70
	v_ashrrev_i32_e32 v19, 31, v18
	v_lshlrev_b64 v[18:19], 7, v[18:19]
	v_lshrrev_b32_e32 v13, 1, v70
	v_lshl_add_u64 v[18:19], s[0:1], 0, v[18:19]
	v_and_b32_e32 v162, 16, v13
	v_lshl_add_u64 v[18:19], v[18:19], 0, v[162:163]
	global_load_dwordx4 v[108:111], v[18:19], off
	global_load_dwordx4 v[104:107], v[18:19], off offset:32
	global_load_dwordx4 v[100:103], v[18:19], off offset:64
	global_load_dwordx4 v[96:99], v[18:19], off offset:96
	v_and_b32_e32 v13, 0xfffff0, v48
	v_lshlrev_b32_e32 v15, 1, v48
	v_and_or_b32 v13, v15, 8, v13
	v_lshrrev_b32_e32 v13, 1, v13
	v_bfe_u32 v17, v20, 5, 2
	v_lshrrev_b32_e32 v15, 1, v48
	v_or_b32_e32 v13, v13, v17
	v_and_b32_e32 v73, 3, v48
	v_lshlrev_b32_e32 v72, 9, v13
	v_and_or_b32 v13, v15, 4, v73
	v_and_b32_e32 v15, 0xfffff0, v12
	v_lshlrev_b32_e32 v12, 1, v12
	v_and_or_b32 v12, v12, 8, v15
	v_lshrrev_b32_e32 v12, 1, v12
	v_or_b32_e32 v12, v12, v17
	v_lshlrev_b32_e32 v13, 6, v13
	v_and_b32_e32 v74, 48, v71
	v_lshlrev_b32_e32 v75, 9, v12
	v_or3_b32 v18, v72, v13, v74
	v_or3_b32 v17, v75, v13, v74
	v_lshlrev_b32_e32 v12, 7, v14
	v_and_b32_e32 v13, 0x70, v70
	v_bitop3_b32 v76, v16, v12, v13 bitop3:0xde
	v_add_co_u32_e32 v12, vcc, s75, v66
	s_movk_i32 s0, 0x6000
	s_nop 0
	v_addc_co_u32_e32 v13, vcc, 0, v67, vcc
	global_load_dwordx4 v[54:57], v[12:13], off
	v_add_co_u32_e32 v12, vcc, s0, v66
	v_and_b32_e32 v49, 31, v70
	s_nop 0
	v_addc_co_u32_e32 v13, vcc, 0, v67, vcc
	v_add_co_u32_e32 v14, vcc, s45, v68
	v_lshlrev_b32_e32 v80, 7, v49
	s_nop 0
	v_addc_co_u32_e32 v15, vcc, 0, v69, vcc
	global_load_dwordx4 v[58:61], v[12:13], off
	global_load_dwordx4 v[62:65], v[14:15], off
	v_and_b32_e32 v81, 0x70, v20
	v_add_u32_e32 v77, 0, v18
	v_add_u32_e32 v78, 0, v17
	v_bitop3_b32 v171, v162, v80, v81 bitop3:0xde
	s_waitcnt vmcnt(3)
	v_add_u32_e32 v79, 0, v76
	v_or_b32_e32 v83, 32, v162
	s_add_i32 s48, 0, 0x12000
	v_bitop3_b32 v175, v83, v80, v81 bitop3:0xde
	v_and_b32_e32 v82, 63, v70
	s_mov_b32 s0, 0xa000
	v_and_b32_e32 v177, 0xc0, v71
	v_or_b32_e32 v71, 64, v162
	v_bitop3_b32 v174, v71, v80, v81 bitop3:0xde
	v_or_b32_e32 v84, 0x60, v162
	v_bitop3_b32 v173, v84, v80, v81 bitop3:0xde
	s_mov_b32 s8, 0
	s_mov_b32 s9, s8
	s_mov_b32 s10, s8
	s_mov_b32 s11, s8
	s_mov_b32 s12, s8
	s_mov_b32 s13, s8
	s_mov_b32 s14, s8
	s_mov_b32 s15, s8
	s_mov_b32 s16, s8
	s_mov_b32 s17, s8
	s_waitcnt vmcnt(9)
	ds_write_b128 v77, v[0:3]
	s_waitcnt vmcnt(8)
	ds_write_b128 v78, v[4:7]
	v_add_u32_e32 v4, 0, v171
	s_waitcnt vmcnt(7)
	ds_write_b128 v79, v[8:11] offset:49152
	s_waitcnt lgkmcnt(0)
	s_barrier
	ds_read_b128 v[0:3], v4 offset:49152
	ds_read_b128 v[4:7], v4 offset:53248
	v_and_b32_e32 v8, 0x3fffffc0, v70
	v_lshl_add_u32 v168, v8, 2, s48
	v_add_u32_e32 v8, 0, v175
	s_waitcnt vmcnt(6) lgkmcnt(1)
	v_mfma_f32_32x32x16_bf16 v[16:31], v[0:3], v[108:111], 0
	ds_read_b128 v[0:3], v8 offset:49152
	s_mov_b32 s18, s8
	s_mov_b32 s19, s8
	s_mov_b32 s20, s8
	s_mov_b32 s21, s8
	s_mov_b32 s22, s8
	s_mov_b32 s23, s8
	s_waitcnt lgkmcnt(1)
	v_mfma_f32_32x32x16_bf16 v[32:47], v[4:7], v[108:111], 0
	v_lshlrev_b32_e32 v4, 3, v82
	v_lshlrev_b32_e32 v5, 1, v70
	v_and_b32_e32 v176, 24, v4
	v_and_b32_e32 v178, 32, v5
	v_and_b32_e32 v179, 0x100, v4
	ds_read_b128 v[4:7], v8 offset:53248
	v_add_co_u32_e32 v8, vcc, s75, v68
	s_waitcnt vmcnt(5) lgkmcnt(0)
	v_mfma_f32_32x32x16_bf16 v[32:47], v[4:7], v[104:107], v[32:47]
	v_addc_co_u32_e32 v9, vcc, 0, v69, vcc
	v_add_co_u32_e32 v10, vcc, s0, v66
	s_mov_b32 s0, 0x8000
	s_nop 0
	v_addc_co_u32_e32 v11, vcc, 0, v67, vcc
	v_add_co_u32_e32 v4, vcc, s0, v66
	v_add_u32_e32 v6, 0, v174
	s_nop 0
	v_addc_co_u32_e32 v5, vcc, 0, v67, vcc
	v_mfma_f32_32x32x16_bf16 v[16:31], v[0:3], v[104:107], v[16:31]
	ds_read_b128 v[0:3], v6 offset:49152
	global_load_dwordx4 v[120:123], v[8:9], off
	global_load_dwordx4 v[112:115], v[10:11], off
	global_load_dwordx4 v[116:119], v[4:5], off
	v_add_u32_e32 v8, 0, v173
	ds_read_b128 v[4:7], v6 offset:53248
	ds_read_b128 v[66:69], v8 offset:53248
	s_mov_b32 s0, 0x10000
	s_waitcnt vmcnt(7) lgkmcnt(2)
; #define SWRITE(b, i) do { *(bf16x8*)(V_lds + (b) * AT_SHM_V + vst0) = sr_[i].vs0; *(bf16x8*)(V_lds + (b) * AT_SHM_V + vst1) = sr_[i].vs1; \
;     *(bf16x8*)(K_lds + (b) * AT_SHM_K + kst) = sr_[i].ks0; } while (0)
; #define SWAIT() asm volatile("s_waitcnt vmcnt(3)" ::: "memory")
; DEV void partialSM(f32x16& p0, f32x16& p1, float& m_reg, float& mn, float& alpha) {
;   constexpr float C = AT_SCALE * 1.4426950408889634f;
;   float pmax = p0[0];
; #pragma unroll
;   for (int r = 1; r < 16; ++r) pmax = fmaxf(pmax, p0[r]);
; #pragma unroll
;   for (int r = 0; r < 16; ++r) pmax = fmaxf(pmax, p1[r]);
;   { auto rr = __builtin_amdgcn_permlane32_swap(__float_as_uint(pmax), __float_as_uint(pmax), false, false);
;     pmax = fmaxf(__uint_as_float(rr[0]), __uint_as_float(rr[1])); }
;   if (__builtin_expect(__all(pmax - m_reg <= AT_THR / AT_SCALE), 1)) { mn = m_reg; alpha = 1.f; }
;   else { mn = fmaxf(m_reg, pmax); alpha = __builtin_amdgcn_exp2f((m_reg - mn) * C); m_reg = mn; }
;   float mnC = -mn * C;
; #pragma unroll
;   for (int r = 0; r < 16; ++r) p0[r] = fmaf(p0[r], C, mnC);
; #pragma unroll
;   for (int r = 0; r < 16; ++r) p1[r] = fmaf(p1[r], C, mnC);
; #pragma unroll
;   for (int r = 0; r < 16; ++r) p0[r] = __builtin_amdgcn_exp2f(p0[r]);
; DEV void attn_pass(const u16* __restrict__ Qb, const u16* __restrict__ Kh, const u16* __restrict__ Vh, int seq, f32x16* o, float* rli) {
;     ...
;   qkt(pA0, pA1, K_lds, qr, r32, hi); partialSM(pA0, pA1, m_reg, mnA, alA);
;   SWAIT(); SWRITE(1, SO); __syncthreads();
	v_mfma_f32_32x32x16_bf16 v[16:31], v[0:3], v[100:103], v[16:31]
	ds_read_b128 v[0:3], v8 offset:49152
	s_waitcnt vmcnt(3)
	s_waitcnt vmcnt(5)
	ds_write_b128 v77, v[54:57] offset:16384
	s_waitcnt vmcnt(4)
	ds_write_b128 v78, v[58:61] offset:16384
	s_waitcnt vmcnt(3)
	ds_write_b128 v79, v[62:65] offset:57344
	v_mov_b32_e32 v54, 0xf149f2ca
	v_bitop3_b32 v183, v162, s0, v81 bitop3:0xde
	v_bitop3_b32 v185, v83, s0, v81 bitop3:0xde
	v_bitop3_b32 v199, v71, s0, v81 bitop3:0xde
	s_waitcnt lgkmcnt(5)
	v_mfma_f32_32x32x16_bf16 v[32:47], v[4:7], v[100:103], v[32:47]
	v_bitop3_b32 v201, v84, s0, v81 bitop3:0xde
	v_lshl_add_u32 v169, v49, 2, v168
	s_mov_b32 s45, 4
	s_mov_b32 s50, 3
	s_mov_b32 s51, 1
	s_mov_b32 s66, 2
	v_cmp_gt_u32_e64 s[6:7], 32, v82
	s_waitcnt lgkmcnt(3)
	v_mfma_f32_32x32x16_bf16 v[16:31], v[0:3], v[96:99], v[16:31]
	v_mov_b64_e32 v[0:1], s[8:9]
	v_mov_b64_e32 v[2:3], s[10:11]
	v_mov_b64_e32 v[4:5], s[12:13]
	v_mov_b64_e32 v[6:7], s[14:15]
	v_mov_b64_e32 v[8:9], s[16:17]
	v_mov_b64_e32 v[10:11], s[18:19]
	v_mov_b64_e32 v[12:13], s[20:21]
	v_mfma_f32_32x32x16_bf16 v[32:47], v[66:69], v[96:99], v[32:47]
	s_nop 3
	v_max_f32_e32 v66, v17, v17
	v_max_f32_e32 v67, v16, v16
	v_max_f32_e32 v66, v67, v66
	v_max3_f32 v66, v66, v18, v19
	v_max3_f32 v66, v66, v20, v21
	v_max3_f32 v66, v66, v22, v23
	v_max3_f32 v66, v66, v24, v25
	v_max3_f32 v66, v66, v26, v27
	v_max3_f32 v66, v66, v28, v29
	v_max3_f32 v66, v66, v30, v31
	v_max3_f32 v66, v66, v32, v33
	v_max3_f32 v66, v66, v34, v35
	v_max3_f32 v66, v66, v36, v37
	v_max3_f32 v66, v66, v38, v39
	v_max3_f32 v66, v66, v40, v41
	v_max3_f32 v66, v66, v42, v43
	v_max3_f32 v66, v66, v44, v45
	v_max3_f32 v66, v66, v46, v47
	v_mov_b32_e32 v67, v66
	s_nop 1
	v_permlane32_swap_b32_e32 v66, v67
	v_max_f32_e32 v67, v67, v67
	v_max_f32_e32 v66, v66, v66
	v_max_f32_e32 v66, v66, v67
	v_mov_b64_e32 v[14:15], s[22:23]
	v_add_f32_e32 v67, 0x7149f2ca, v66
	s_mov_b32 s18, 0x4138aa3b
	v_cmp_ge_f32_e32 vcc, s18, v67
	s_cmp_eq_u64 vcc, exec
	v_max_f32_e32 v55, 0xf149f2ca, v66
	s_cselect_b64 vcc, -1, 0
	v_cndmask_b32_e32 v140, v55, v54, vcc
	v_mul_f32_e32 v54, 0xbf800000, v140
	v_mov_b32_e32 v236, v54
	v_mov_b32_e32 v237, v54
	v_mov_b32_e32 v238, v54
	v_mov_b32_e32 v239, v54
	v_mov_b32_e32 v240, v54
	v_mov_b32_e32 v241, v54
	v_mov_b32_e32 v242, v54
	v_mov_b32_e32 v243, v54
	v_mov_b32_e32 v244, v54
	v_mov_b32_e32 v245, v54
	v_mov_b32_e32 v246, v54
	v_mov_b32_e32 v247, v54
	v_mov_b32_e32 v248, v54
	v_mov_b32_e32 v249, v54
	v_mov_b32_e32 v250, v54
	v_mov_b32_e32 v251, v54
	v_fmamk_f32 v16, v16, 0x3f800000, v54
	v_exp_f32_e32 v150, v16
	v_fmamk_f32 v16, v17, 0x3f800000, v54
	v_exp_f32_e32 v160, v16
	v_fmamk_f32 v16, v18, 0x3f800000, v54
	v_exp_f32_e32 v151, v16
	v_fmamk_f32 v16, v19, 0x3f800000, v54
	v_exp_f32_e32 v161, v16
	v_fmamk_f32 v16, v20, 0x3f800000, v54
	v_exp_f32_e32 v158, v16
	v_fmamk_f32 v16, v21, 0x3f800000, v54
	v_exp_f32_e32 v214, v16
	v_fmamk_f32 v16, v22, 0x3f800000, v54
	v_exp_f32_e32 v159, v16
	v_fmamk_f32 v16, v23, 0x3f800000, v54
	v_exp_f32_e32 v215, v16
	v_fmamk_f32 v16, v24, 0x3f800000, v54
	v_exp_f32_e32 v142, v16
	v_fmamk_f32 v16, v25, 0x3f800000, v54
	v_exp_f32_e32 v146, v16
	v_fmamk_f32 v16, v26, 0x3f800000, v54
	v_exp_f32_e32 v143, v16
	v_fmamk_f32 v16, v27, 0x3f800000, v54
	v_exp_f32_e32 v147, v16
	v_fmamk_f32 v16, v28, 0x3f800000, v54
	v_exp_f32_e32 v144, v16
	v_fmamk_f32 v16, v29, 0x3f800000, v54
	v_exp_f32_e32 v148, v16
	v_fmamk_f32 v16, v30, 0x3f800000, v54
	v_exp_f32_e32 v145, v16
	v_add3_u32 v16, v179, 0, v177
	v_add3_u32 v184, v16, v178, v176
	v_lshlrev_b32_e32 v16, 5, v48
	v_and_b32_e32 v16, 0x100, v16
	v_lshlrev_b32_e32 v17, 6, v73
	v_or3_b32 v18, v75, v16, v17
	v_or3_b32 v19, v72, v16, v17
	v_mov_b32_e32 v16, 0x88000
	v_pk_fma_f32 v[132:133], v[38:39], s[86:87], v[54:55] op_sel_hi:[1,0,0]
	v_sub_f32_e32 v38, 0xf149f2ca, v55
	v_mad_i64_i32 v[16:17], s[0:1], s47, v16, v[52:53]
	v_and_b32_e32 v20, 7, v70
	v_mul_f32_e32 v38, 0x3f800000, v38
	v_lshl_or_b32 v16, v20, 4, v16
	v_exp_f32_e32 v38, v38
	v_lshl_add_u64 v[154:155], s[96:97], 0, v[16:17]
	v_mov_b32_e32 v16, 0x110000
	v_pk_fma_f32 v[124:125], v[46:47], s[86:87], v[54:55] op_sel_hi:[1,0,0]
	v_pk_fma_f32 v[126:127], v[44:45], s[86:87], v[54:55] op_sel_hi:[1,0,0]
	v_pk_fma_f32 v[128:129], v[42:43], s[86:87], v[54:55] op_sel_hi:[1,0,0]
	v_pk_fma_f32 v[130:131], v[40:41], s[86:87], v[54:55] op_sel_hi:[1,0,0]
	v_pk_fma_f32 v[134:135], v[36:37], s[86:87], v[54:55] op_sel_hi:[1,0,0]
	v_pk_fma_f32 v[136:137], v[34:35], s[86:87], v[54:55] op_sel_hi:[1,0,0]
	v_pk_fma_f32 v[138:139], v[32:33], s[86:87], v[54:55] op_sel_hi:[1,0,0]
	v_fmac_f32_e32 v54, 0x3f800000, v31
	v_mad_i64_i32 v[16:17], s[0:1], s49, v16, v[50:51]
	v_and_b32_e32 v20, 15, v70
	v_exp_f32_e32 v149, v54
	v_lshl_or_b32 v16, v20, 4, v16
	s_add_i32 s49, 0, 0x4000
	v_lshl_add_u64 v[156:157], s[96:97], 0, v[16:17]
	v_add3_u32 v16, v179, s49, v177
	v_cndmask_b32_e64 v182, v38, 1.0, vcc
	s_mov_b32 s9, 0xe000
	v_add_u32_e32 v203, 0x8000, v18
	v_add_u32_e32 v204, 0x8000, v19
	v_add_u32_e32 v206, 0xc000, v18
	v_add_u32_e32 v207, 0xc000, v19
	v_add3_u32 v208, v16, v178, v176
	v_mov_b64_e32 v[62:63], v[14:15]
	v_mov_b64_e32 v[46:47], v[14:15]
	v_mov_b64_e32 v[30:31], v[14:15]
	v_add_u32_e32 v180, 0x10000, v76
	v_add_u32_e32 v181, 0, v80
	v_bitop3_b32 v198, v162, s9, v81 bitop3:0xde
	v_bitop3_b32 v200, v83, s9, v81 bitop3:0xde
	v_add_u32_e32 v202, 0, v74
	v_add_u32_e32 v205, 0x12000, v76
	v_bitop3_b32 v209, v71, s9, v81 bitop3:0xde
	v_bitop3_b32 v210, v84, s9, v81 bitop3:0xde
	v_mov_b32_e32 v170, 0
	s_mov_b32 s9, s8
	v_mov_b64_e32 v[60:61], v[12:13]
	v_mov_b64_e32 v[58:59], v[10:11]
	v_mov_b64_e32 v[56:57], v[8:9]
	v_mov_b64_e32 v[54:55], v[6:7]
	v_mov_b64_e32 v[52:53], v[4:5]
	v_mov_b64_e32 v[50:51], v[2:3]
	v_mov_b64_e32 v[48:49], v[0:1]
	v_mov_b64_e32 v[44:45], v[12:13]
	v_mov_b64_e32 v[42:43], v[10:11]
	v_mov_b64_e32 v[40:41], v[8:9]
	v_mov_b64_e32 v[38:39], v[6:7]
	v_mov_b64_e32 v[36:37], v[4:5]
	v_mov_b64_e32 v[34:35], v[2:3]
	v_mov_b64_e32 v[32:33], v[0:1]
	v_mov_b64_e32 v[28:29], v[12:13]
	v_mov_b64_e32 v[26:27], v[10:11]
	v_mov_b64_e32 v[24:25], v[8:9]
	v_mov_b64_e32 v[22:23], v[6:7]
	v_mov_b64_e32 v[20:21], v[4:5]
	v_mov_b64_e32 v[18:19], v[2:3]
	v_mov_b64_e32 v[16:17], v[0:1]
	v_readfirstlane_b32 s0, v252
	s_nop 1
	s_cmp_lt_u32 s0, 0x100
	s_cbranch_scc1 .Lprio_a
	s_setprio 1
.Lprio_a:
	s_waitcnt lgkmcnt(0)
	s_barrier

; #define SBAR() __builtin_amdgcn_sched_barrier(0)
; DEV void finishSM(f32x16& p0, f32x16& p1, float alpha, float& l_reg, bf16x8& pa0, bf16x8& pa1, bf16x8& pa2, bf16x8& pa3) {
; #pragma unroll
;   for (int r = 0; r < 16; ++r) p1[r] = __builtin_amdgcn_exp2f(p1[r]);
;   float ps = 0;
; #pragma unroll
;   for (int r = 0; r < 16; ++r) ps += p0[r];
; #pragma unroll
;   for (int r = 0; r < 16; ++r) ps += p1[r];
;   { auto rr = __builtin_amdgcn_permlane32_swap(__float_as_uint(ps), __float_as_uint(ps), false, false);
;     ps = __uint_as_float(rr[0]) + __uint_as_float(rr[1]); }
;   l_reg = l_reg * alpha + ps;
;     ...
;   PK4(p0, 0, pa0); PK4(p0, 8, pa1); PK4(p1, 0, pa2); PK4(p1, 8, pa3);
; DEV void attn_pass(const u16* __restrict__ Qb, const u16* __restrict__ Kh, const u16* __restrict__ Vh, int seq, f32x16* o, float* rli) {
;     ...
;   { const int bl = (NT - 1) % 3, bp = (NT - 2) % 3;
;     SBAR(); qkt(pB0, pB1, K_lds + bl * AT_SHM_K, qr, r32, hi);
;     finishSM(pA0, pA1, alA, l_reg, pa0, pa1, pa2, pa3); SBAR();
;     pv_d0(o, vb0 + bp * AT_SHM_V, pa0, pa1, pa2, pa3); partialSM(pB0, pB1, m_reg, mnB, alB);
.LBB0_82:
	s_setprio 0
	v_mov_b32_e32 v140, 0
	s_add_i32 s0, s44, 0xffff
	s_and_b32 s1, s0, 0xff
	s_mulk_i32 s1, 0xab
	s_bfe_u32 s1, s1, 0x70009
	s_mul_i32 s1, s1, 3
	s_sub_i32 s0, s0, s1
	s_and_b32 s10, s0, 0xff
	s_add_i32 s0, s44, 0xfffe
	s_and_b32 s1, s0, 0xff
	s_mulk_i32 s1, 0xab
	s_bfe_u32 s1, s1, 0x70009
	v_or_b32_e32 v64, v176, v177
	s_mul_i32 s1, s1, 3
	v_or3_b32 v64, v64, v178, v179
	s_sub_i32 s0, s0, s1
	v_add_u32_e32 v112, 0, v64
	s_and_b32 s0, s0, 0xff
	s_lshl_b32 s1, s10, 13
	s_add_i32 s45, s1, 0
	v_add_u32_e32 v68, s45, v171
	ds_read_b128 v[64:67], v68 offset:49152
	ds_read_b128 v[68:71], v68 offset:53248
	v_add_u32_e32 v113, s45, v175
	v_exp_f32_e32 v118, v129
	v_exp_f32_e32 v119, v126
	s_waitcnt lgkmcnt(1)
	v_mfma_f32_32x32x16_bf16 v[80:95], v[64:67], v[108:111], v[236:251]
	v_exp_f32_e32 v120, v127
	v_exp_f32_e32 v121, v124
	v_exp_f32_e32 v122, v125
	s_waitcnt lgkmcnt(0)
	v_mfma_f32_32x32x16_bf16 v[64:79], v[68:71], v[108:111], v[236:251]
	ds_read_b128 v[108:111], v113 offset:49152
	ds_read_b128 v[114:117], v113 offset:53248
	v_exp_f32_e32 v113, v132
	s_waitcnt lgkmcnt(1)
	v_mfma_f32_32x32x16_bf16 v[80:95], v[108:111], v[104:107], v[80:95]
	v_add_u32_e32 v108, s45, v174
	s_waitcnt lgkmcnt(0)
	v_mfma_f32_32x32x16_bf16 v[64:79], v[114:117], v[104:107], v[64:79]
	ds_read_b128 v[104:107], v108 offset:49152
	ds_read_b128 v[108:111], v108 offset:53248
	v_exp_f32_e32 v114, v133
	v_exp_f32_e32 v115, v130
	v_exp_f32_e32 v116, v131
	v_exp_f32_e32 v117, v128
	s_waitcnt lgkmcnt(1)
	v_mfma_f32_32x32x16_bf16 v[80:95], v[104:107], v[100:103], v[80:95]
	v_add_u32_e32 v104, s45, v173
	s_waitcnt lgkmcnt(0)
	v_mfma_f32_32x32x16_bf16 v[64:79], v[108:111], v[100:103], v[64:79]
	ds_read_b128 v[100:103], v104 offset:49152
	ds_read_b128 v[104:107], v104 offset:53248
	v_exp_f32_e32 v108, v136
	v_exp_f32_e32 v109, v137
	v_exp_f32_e32 v110, v134
	v_exp_f32_e32 v111, v135
	s_waitcnt lgkmcnt(1)
	v_mfma_f32_32x32x16_bf16 v[80:95], v[100:103], v[96:99], v[80:95]
	v_cvt_pk_bf16_f32 v100, v158, v214
	v_cvt_pk_bf16_f32 v101, v159, v215
	v_cvt_pk_bf16_f32 v102, v142, v146
	v_cvt_pk_bf16_f32 v103, v143, v147
	s_waitcnt lgkmcnt(0)
	v_mfma_f32_32x32x16_bf16 v[64:79], v[104:107], v[96:99], v[64:79]
	v_add_f32_e32 v96, v160, v150
	v_add_f32_e32 v96, v151, v96
	v_add_f32_e32 v96, v161, v96
	v_add_f32_e32 v96, v158, v96
	v_add_f32_e32 v96, v214, v96
	v_add_f32_e32 v96, v159, v96
	v_add_f32_e32 v96, v215, v96
	v_add_f32_e32 v96, v142, v96
	v_add_f32_e32 v96, v146, v96
	v_add_f32_e32 v96, v143, v96
	v_add_f32_e32 v96, v147, v96
	v_exp_f32_e32 v106, v138
	v_add_f32_e32 v96, v144, v96
	v_exp_f32_e32 v107, v139
	v_add_f32_e32 v96, v148, v96
	v_add_f32_e32 v96, v145, v96
	v_add_f32_e32 v96, v149, v96
	v_add_f32_e32 v96, v106, v96
	v_add_f32_e32 v96, v107, v96
	v_add_f32_e32 v96, v108, v96
	v_add_f32_e32 v96, v109, v96
	v_add_f32_e32 v96, v110, v96
	v_add_f32_e32 v96, v111, v96
	v_add_f32_e32 v96, v113, v96
	v_add_f32_e32 v96, v114, v96
	v_add_f32_e32 v96, v115, v96
	v_add_f32_e32 v96, v116, v96
	v_add_f32_e32 v96, v117, v96
	v_add_f32_e32 v96, v118, v96
	v_add_f32_e32 v96, v119, v96
	v_add_f32_e32 v96, v120, v96
	v_add_f32_e32 v96, v121, v96
	v_add_f32_e32 v96, v122, v96
	v_mov_b32_e32 v97, v96
	v_cvt_pk_bf16_f32 v98, v150, v160
	v_cvt_pk_bf16_f32 v99, v151, v161
	s_nop 1
	v_permlane32_swap_b32_e32 v96, v97
	v_permlane32_swap_b32_e32 v98, v100
	v_permlane32_swap_b32_e32 v99, v101
	v_cvt_pk_bf16_f32 v104, v144, v148
	v_cvt_pk_bf16_f32 v105, v145, v149
	v_cvt_pk_bf16_f32 v106, v106, v107
	v_cvt_pk_bf16_f32 v107, v108, v109
	v_cvt_pk_bf16_f32 v108, v110, v111
	v_cvt_pk_bf16_f32 v109, v113, v114
	v_cvt_pk_bf16_f32 v114, v115, v116
	v_cvt_pk_bf16_f32 v115, v117, v118
	v_cvt_pk_bf16_f32 v116, v119, v120
	v_cvt_pk_bf16_f32 v117, v121, v122
	s_nop 0
	v_permlane32_swap_b32_e32 v102, v104
	v_permlane32_swap_b32_e32 v103, v105
	v_permlane32_swap_b32_e32 v106, v108
	v_permlane32_swap_b32_e32 v107, v109
	v_permlane32_swap_b32_e32 v114, v116
	v_permlane32_swap_b32_e32 v115, v117
	s_lshl_b32 s50, s0, 14
	v_add_u32_e32 v110, s50, v112
	ds_read_b64_tr_b16 v[118:119], v110 offset:0
	ds_read_b64_tr_b16 v[120:121], v110 offset:0x800
	ds_read_b64_tr_b16 v[122:123], v110 offset:0x1000
	ds_read_b64_tr_b16 v[124:125], v110 offset:0x1800
	ds_read_b64_tr_b16 v[126:127], v110 offset:0x2000
	ds_read_b64_tr_b16 v[128:129], v110 offset:0x2800
	ds_read_b64_tr_b16 v[130:131], v110 offset:0x3000
	ds_read_b64_tr_b16 v[132:133], v110 offset:0x3800
	s_waitcnt lgkmcnt(0)
	s_nop 0
	v_mfma_f32_32x32x16_bf16 v[0:15], v[98:101], v[118:121], v[0:15]
	ds_read_b64_tr_b16 v[118:119], v110 offset:0x200
	ds_read_b64_tr_b16 v[120:121], v110 offset:0xa00
	v_mfma_f32_32x32x16_bf16 v[0:15], v[102:105], v[122:125], v[0:15]
	ds_read_b64_tr_b16 v[122:123], v110 offset:0x1200
	ds_read_b64_tr_b16 v[124:125], v110 offset:0x1a00
	v_mfma_f32_32x32x16_bf16 v[0:15], v[106:109], v[126:129], v[0:15]
	ds_read_b64_tr_b16 v[126:127], v110 offset:0x2200
	ds_read_b64_tr_b16 v[128:129], v110 offset:0x2a00
	v_mfma_f32_32x32x16_bf16 v[0:15], v[114:117], v[130:133], v[0:15]
	ds_read_b64_tr_b16 v[130:131], v110 offset:0x3200
	ds_read_b64_tr_b16 v[132:133], v110 offset:0x3a00
	s_waitcnt lgkmcnt(0)
; #define RESC(a) do { if (__any((a) < 1.f)) { if (hi == 0) al_l[r32] = (a); asm volatile("s_waitcnt lgkmcnt(0)" ::: "memory"); \
;     for (int d = 0; d < 4; ++d) for (int r = 0; r < 16; ++r) o[d][r] *= al_l[crow(r, hi)]; } } while (0)
; DEV void partialSM(f32x16& p0, f32x16& p1, float& m_reg, float& mn, float& alpha) {
;   constexpr float C = AT_SCALE * 1.4426950408889634f;
;   float pmax = p0[0];
; #pragma unroll
;   for (int r = 1; r < 16; ++r) pmax = fmaxf(pmax, p0[r]);
; #pragma unroll
;   for (int r = 0; r < 16; ++r) pmax = fmaxf(pmax, p1[r]);
;   { auto rr = __builtin_amdgcn_permlane32_swap(__float_as_uint(pmax), __float_as_uint(pmax), false, false);
;     pmax = fmaxf(__uint_as_float(rr[0]), __uint_as_float(rr[1])); }
;   if (__builtin_expect(__all(pmax - m_reg <= AT_THR / AT_SCALE), 1)) { mn = m_reg; alpha = 1.f; }
;   else { mn = fmaxf(m_reg, pmax); alpha = __builtin_amdgcn_exp2f((m_reg - mn) * C); m_reg = mn; }
; DEV void attn_pass(const u16* __restrict__ Qb, const u16* __restrict__ Kh, const u16* __restrict__ Vh, int seq, f32x16* o, float* rli) {
;     ...
;     pv_d0(o, vb0 + bp * AT_SHM_V, pa0, pa1, pa2, pa3); partialSM(pB0, pB1, m_reg, mnB, alB);
;     RESC(alB);
	v_mfma_f32_32x32x16_bf16 v[48:63], v[98:101], v[118:121], v[48:63]
	ds_read_b64_tr_b16 v[118:119], v110 offset:0x400
	ds_read_b64_tr_b16 v[120:121], v110 offset:0xc00
	v_mfma_f32_32x32x16_bf16 v[48:63], v[102:105], v[122:125], v[48:63]
	ds_read_b64_tr_b16 v[122:123], v110 offset:0x1400
	ds_read_b64_tr_b16 v[124:125], v110 offset:0x1c00
	v_mfma_f32_32x32x16_bf16 v[48:63], v[106:109], v[126:129], v[48:63]
	ds_read_b64_tr_b16 v[126:127], v110 offset:0x2400
	ds_read_b64_tr_b16 v[128:129], v110 offset:0x2c00
	v_mfma_f32_32x32x16_bf16 v[48:63], v[114:117], v[130:133], v[48:63]
	ds_read_b64_tr_b16 v[130:131], v110 offset:0x3400
	ds_read_b64_tr_b16 v[132:133], v110 offset:0x3c00
	s_waitcnt lgkmcnt(0)
	v_mfma_f32_32x32x16_bf16 v[32:47], v[98:101], v[118:121], v[32:47]
	ds_read_b64_tr_b16 v[118:119], v110 offset:0x600
	ds_read_b64_tr_b16 v[120:121], v110 offset:0xe00
	v_mfma_f32_32x32x16_bf16 v[32:47], v[102:105], v[122:125], v[32:47]
	ds_read_b64_tr_b16 v[122:123], v110 offset:0x1600
	ds_read_b64_tr_b16 v[124:125], v110 offset:0x1e00
	v_mfma_f32_32x32x16_bf16 v[32:47], v[106:109], v[126:129], v[32:47]
	ds_read_b64_tr_b16 v[126:127], v110 offset:0x2600
	ds_read_b64_tr_b16 v[128:129], v110 offset:0x2e00
	v_mfma_f32_32x32x16_bf16 v[32:47], v[114:117], v[130:133], v[32:47]
	ds_read_b64_tr_b16 v[130:131], v110 offset:0x3600
	ds_read_b64_tr_b16 v[132:133], v110 offset:0x3e00
	s_waitcnt lgkmcnt(0)
	v_mfma_f32_32x32x16_bf16 v[16:31], v[98:101], v[118:121], v[16:31]
	v_max_f32_e32 v98, v81, v81
	v_max_f32_e32 v99, v80, v80
	v_max_f32_e32 v98, v99, v98
	v_max3_f32 v98, v98, v82, v83
	v_max3_f32 v98, v98, v84, v85
	v_max3_f32 v98, v98, v86, v87
	v_max3_f32 v98, v98, v88, v89
	v_max3_f32 v98, v98, v90, v91
	v_max3_f32 v98, v98, v92, v93
	v_mfma_f32_32x32x16_bf16 v[16:31], v[102:105], v[122:125], v[16:31]
	v_max3_f32 v98, v98, v94, v95
	v_max3_f32 v98, v98, v64, v65
	v_max3_f32 v98, v98, v66, v67
	v_max3_f32 v98, v98, v68, v69
	v_max3_f32 v98, v98, v70, v71
	v_max3_f32 v98, v98, v72, v73
	v_max3_f32 v98, v98, v74, v75
	v_max3_f32 v98, v98, v76, v77
	v_mfma_f32_32x32x16_bf16 v[16:31], v[106:109], v[126:129], v[16:31]
	v_max3_f32 v98, v98, v78, v79
	v_mov_b32_e32 v99, v98
	s_nop 1
	v_permlane32_swap_b32_e32 v98, v99
	v_max_f32_e32 v99, v99, v99
	v_max_f32_e32 v98, v98, v98
	v_max_f32_e32 v98, v98, v99
	v_sub_f32_e32 v99, v98, v140
	v_cmp_ge_f32_e32 vcc, s18, v99
	v_max_f32_e32 v99, v140, v140
	v_max_f32_e32 v99, v99, v98
	v_mfma_f32_32x32x16_bf16 v[16:31], v[114:117], v[130:133], v[16:31]
	v_sub_f32_e32 v98, v140, v99
	v_mul_f32_e32 v98, 0x3f800000, v98
	v_exp_f32_e32 v98, v98
	s_cmp_eq_u64 vcc, exec
	s_cselect_b64 s[0:1], -1, 0
	v_cndmask_b32_e64 v98, v98, 1.0, s[0:1]
	v_cmp_gt_f32_e32 vcc, 1.0, v98
	s_cbranch_vccz .LBB0_86
	s_and_saveexec_b64 s[8:9], s[6:7]
	s_mov_b32 s66, 0x800000
	ds_write_b32 v169, v98 offset:128
	s_or_b64 exec, exec, s[8:9]
	s_waitcnt lgkmcnt(0)
	v_add_u32_e32 v113, v168, v162
	ds_read_b128 v[100:103], v113 offset:224
	ds_read_b128 v[104:107], v113 offset:192
	ds_read_b128 v[108:111], v113 offset:160
	ds_read_b128 v[114:117], v113 offset:128
	s_waitcnt lgkmcnt(3)
	v_pk_mul_f32 v[12:13], v[12:13], v[100:101]
	s_waitcnt lgkmcnt(2)
	v_pk_mul_f32 v[8:9], v[8:9], v[104:105]
	s_waitcnt lgkmcnt(1)
	v_pk_mul_f32 v[4:5], v[4:5], v[108:109]
	v_pk_mul_f32 v[14:15], v[14:15], v[102:103]
	v_pk_mul_f32 v[10:11], v[10:11], v[106:107]
	v_pk_mul_f32 v[6:7], v[6:7], v[110:111]
	s_waitcnt lgkmcnt(0)
	v_pk_mul_f32 v[2:3], v[2:3], v[116:117]
	v_pk_mul_f32 v[0:1], v[0:1], v[114:115]
	v_pk_mul_f32 v[60:61], v[60:61], v[100:101]
	v_pk_mul_f32 v[56:57], v[56:57], v[104:105]
	v_pk_mul_f32 v[52:53], v[52:53], v[108:109]
	v_pk_mul_f32 v[62:63], v[62:63], v[102:103]
	v_pk_mul_f32 v[58:59], v[58:59], v[106:107]
	v_pk_mul_f32 v[54:55], v[54:55], v[110:111]
	v_pk_mul_f32 v[50:51], v[50:51], v[116:117]
	v_pk_mul_f32 v[48:49], v[48:49], v[114:115]
	v_pk_mul_f32 v[44:45], v[44:45], v[100:101]
	v_pk_mul_f32 v[40:41], v[40:41], v[104:105]
	v_pk_mul_f32 v[36:37], v[36:37], v[108:109]
	v_pk_mul_f32 v[46:47], v[46:47], v[102:103]
	v_pk_mul_f32 v[42:43], v[42:43], v[106:107]
	v_pk_mul_f32 v[38:39], v[38:39], v[110:111]
	v_pk_mul_f32 v[34:35], v[34:35], v[116:117]
	v_pk_mul_f32 v[32:33], v[32:33], v[114:115]
	v_pk_mul_f32 v[28:29], v[28:29], v[100:101]
	v_pk_mul_f32 v[24:25], v[24:25], v[104:105]
	v_pk_mul_f32 v[20:21], v[20:21], v[108:109]
	v_pk_mul_f32 v[30:31], v[30:31], v[102:103]
	v_pk_mul_f32 v[26:27], v[26:27], v[106:107]
	v_pk_mul_f32 v[22:23], v[22:23], v[110:111]
	v_pk_mul_f32 v[18:19], v[18:19], v[116:117]
	v_pk_mul_f32 v[16:17], v[16:17], v[114:115]
	s_branch .LBB0_87

; #define SBAR() __builtin_amdgcn_sched_barrier(0)
; #define RESC(a) do { if (__any((a) < 1.f)) { if (hi == 0) al_l[r32] = (a); asm volatile("s_waitcnt lgkmcnt(0)" ::: "memory"); \
;     for (int d = 0; d < 4; ++d) for (int r = 0; r < 16; ++r) o[d][r] *= al_l[crow(r, hi)]; } } while (0)
; DEV void partialSM(f32x16& p0, f32x16& p1, float& m_reg, float& mn, float& alpha) {
;     ...
;   float mnC = -mn * C;
; #pragma unroll
;   for (int r = 0; r < 16; ++r) p0[r] = fmaf(p0[r], C, mnC);
; #pragma unroll
;   for (int r = 0; r < 16; ++r) p1[r] = fmaf(p1[r], C, mnC);
; #pragma unroll
;   for (int r = 0; r < 16; ++r) p0[r] = __builtin_amdgcn_exp2f(p0[r]);
; }
; DEV void finishSM(f32x16& p0, f32x16& p1, float alpha, float& l_reg, bf16x8& pa0, bf16x8& pa1, bf16x8& pa2, bf16x8& pa3) {
; #pragma unroll
;   for (int r = 0; r < 16; ++r) p1[r] = __builtin_amdgcn_exp2f(p1[r]);
;   float ps = 0;
; #pragma unroll
;   for (int r = 0; r < 16; ++r) ps += p0[r];
; #pragma unroll
;   for (int r = 0; r < 16; ++r) ps += p1[r];
;   { auto rr = __builtin_amdgcn_permlane32_swap(__float_as_uint(ps), __float_as_uint(ps), false, false);
;     ps = __uint_as_float(rr[0]) + __uint_as_float(rr[1]); }
;   l_reg = l_reg * alpha + ps;
;     ...
;   PK4(p0, 0, pa0); PK4(p0, 8, pa1); PK4(p1, 0, pa2); PK4(p1, 8, pa3);
; DEV void attn_pass(const u16* __restrict__ Qb, const u16* __restrict__ Kh, const u16* __restrict__ Vh, int seq, f32x16* o, float* rli) {
;     ...
;     RESC(alB);
;     finishSM(pB0, pB1, alB, l_reg, pa0, pa1, pa2, pa3); SBAR();
;     pv_d0(o, vb0 + bl * AT_SHM_V, pa0, pa1, pa2, pa3); }
.LBB0_87:
	v_cndmask_b32_e64 v99, v99, v140, s[0:1]
	v_mul_f32_e32 v99, 0xbf800000, v99
	v_fmamk_f32 v80, v80, 0x3f800000, v99
	v_fmamk_f32 v81, v81, 0x3f800000, v99
	v_fmamk_f32 v82, v82, 0x3f800000, v99
	v_fmamk_f32 v83, v83, 0x3f800000, v99
	v_fmamk_f32 v84, v84, 0x3f800000, v99
	v_fmamk_f32 v85, v85, 0x3f800000, v99
	v_fmamk_f32 v86, v86, 0x3f800000, v99
	v_fmamk_f32 v87, v87, 0x3f800000, v99
	v_fmamk_f32 v88, v88, 0x3f800000, v99
	v_fmamk_f32 v89, v89, 0x3f800000, v99
	v_fmamk_f32 v90, v90, 0x3f800000, v99
	v_fmamk_f32 v91, v91, 0x3f800000, v99
	v_fmamk_f32 v92, v92, 0x3f800000, v99
	v_fmamk_f32 v93, v93, 0x3f800000, v99
	v_fmamk_f32 v94, v94, 0x3f800000, v99
	v_fmamk_f32 v95, v95, 0x3f800000, v99
	v_fmamk_f32 v64, v64, 0x3f800000, v99
	v_fmamk_f32 v65, v65, 0x3f800000, v99
	v_fmamk_f32 v66, v66, 0x3f800000, v99
	v_fmamk_f32 v67, v67, 0x3f800000, v99
	v_fmamk_f32 v68, v68, 0x3f800000, v99
	v_fmamk_f32 v69, v69, 0x3f800000, v99
	v_fmamk_f32 v70, v70, 0x3f800000, v99
	v_fmamk_f32 v71, v71, 0x3f800000, v99
	v_fmamk_f32 v72, v72, 0x3f800000, v99
	v_fmamk_f32 v73, v73, 0x3f800000, v99
	v_fmamk_f32 v74, v74, 0x3f800000, v99
	v_fmamk_f32 v75, v75, 0x3f800000, v99
	v_fmamk_f32 v76, v76, 0x3f800000, v99
	v_fmamk_f32 v77, v77, 0x3f800000, v99
	v_fmamk_f32 v78, v78, 0x3f800000, v99
	v_fmac_f32_e32 v99, 0x3f800000, v79
	v_exp_f32_e32 v79, v80
	v_exp_f32_e32 v80, v81
	v_exp_f32_e32 v81, v82
	v_exp_f32_e32 v82, v83
	v_exp_f32_e32 v83, v84
	v_exp_f32_e32 v84, v85
	v_exp_f32_e32 v85, v86
	v_exp_f32_e32 v86, v87
	v_exp_f32_e32 v87, v88
	v_exp_f32_e32 v88, v89
	v_exp_f32_e32 v89, v90
	v_exp_f32_e32 v90, v91
	v_exp_f32_e32 v91, v92
	v_exp_f32_e32 v92, v93
	v_exp_f32_e32 v93, v94
	v_exp_f32_e32 v94, v95
	v_exp_f32_e32 v95, v64
	v_add_f32_e32 v64, v80, v79
	v_add_f32_e32 v64, v81, v64
	v_add_f32_e32 v64, v82, v64
	v_add_f32_e32 v64, v83, v64
	v_add_f32_e32 v64, v84, v64
	v_add_f32_e32 v64, v85, v64
	v_add_f32_e32 v64, v86, v64
	v_add_f32_e32 v64, v87, v64
	v_add_f32_e32 v64, v88, v64
	v_add_f32_e32 v64, v89, v64
	v_add_f32_e32 v64, v90, v64
	v_add_f32_e32 v64, v91, v64
	v_exp_f32_e32 v100, v65
	v_add_f32_e32 v64, v92, v64
	v_exp_f32_e32 v101, v66
	v_add_f32_e32 v64, v93, v64
	v_exp_f32_e32 v102, v67
	v_add_f32_e32 v64, v94, v64
	v_exp_f32_e32 v103, v68
	v_add_f32_e32 v64, v95, v64
	v_exp_f32_e32 v104, v69
	v_add_f32_e32 v64, v100, v64
	v_exp_f32_e32 v105, v70
	v_add_f32_e32 v64, v101, v64
	v_exp_f32_e32 v106, v71
	v_add_f32_e32 v64, v102, v64
	v_exp_f32_e32 v107, v72
	v_add_f32_e32 v64, v103, v64
	v_exp_f32_e32 v108, v73
	v_add_f32_e32 v64, v104, v64
	v_exp_f32_e32 v109, v74
	v_add_f32_e32 v64, v105, v64
	v_exp_f32_e32 v110, v75
	v_add_f32_e32 v64, v106, v64
	v_exp_f32_e32 v111, v76
	v_add_f32_e32 v64, v107, v64
	v_exp_f32_e32 v113, v77
	v_add_f32_e32 v64, v108, v64
	v_exp_f32_e32 v114, v78
	v_add_f32_e32 v64, v109, v64
	v_exp_f32_e32 v99, v99
	v_add_f32_e32 v64, v110, v64
	v_add_f32_e32 v64, v111, v64
	v_add_f32_e32 v64, v113, v64
	v_add_f32_e32 v64, v114, v64
	v_add_f32_e32 v64, v99, v64
	v_mov_b32_e32 v65, v64
	s_nop 1
	v_permlane32_swap_b32_e32 v64, v65
	v_cvt_pk_bf16_f32 v66, v79, v80
	v_cvt_pk_bf16_f32 v67, v81, v82
	v_cvt_pk_bf16_f32 v68, v83, v84
	v_cvt_pk_bf16_f32 v69, v85, v86
	v_cvt_pk_bf16_f32 v70, v87, v88
	v_cvt_pk_bf16_f32 v71, v89, v90
	v_cvt_pk_bf16_f32 v72, v91, v92
	v_cvt_pk_bf16_f32 v73, v93, v94
	v_cvt_pk_bf16_f32 v74, v95, v100
	v_cvt_pk_bf16_f32 v75, v101, v102
	v_cvt_pk_bf16_f32 v76, v103, v104
	v_cvt_pk_bf16_f32 v77, v105, v106
	v_cvt_pk_bf16_f32 v78, v107, v108
	v_cvt_pk_bf16_f32 v79, v109, v110
	v_cvt_pk_bf16_f32 v80, v111, v113
	v_cvt_pk_bf16_f32 v81, v114, v99
	s_nop 0
	v_permlane32_swap_b32_e32 v66, v68
	v_permlane32_swap_b32_e32 v67, v69
	v_permlane32_swap_b32_e32 v70, v72
	v_permlane32_swap_b32_e32 v71, v73
	v_permlane32_swap_b32_e32 v74, v76
	v_permlane32_swap_b32_e32 v75, v77
	v_permlane32_swap_b32_e32 v78, v80
	v_permlane32_swap_b32_e32 v79, v81
	s_lshl_b32 s51, s10, 14
	v_add_u32_e32 v94, s51, v112
	ds_read_b64_tr_b16 v[82:83], v94 offset:0
	ds_read_b64_tr_b16 v[84:85], v94 offset:0x800
	ds_read_b64_tr_b16 v[86:87], v94 offset:0x1000
	ds_read_b64_tr_b16 v[88:89], v94 offset:0x1800
	ds_read_b64_tr_b16 v[90:91], v94 offset:0x2000
	ds_read_b64_tr_b16 v[92:93], v94 offset:0x2800
	ds_read_b64_tr_b16 v[100:101], v94 offset:0x3000
	ds_read_b64_tr_b16 v[102:103], v94 offset:0x3800
	s_waitcnt lgkmcnt(0)
	s_nop 0
	v_mfma_f32_32x32x16_bf16 v[0:15], v[66:69], v[82:85], v[0:15]
	ds_read_b64_tr_b16 v[82:83], v94 offset:0x200
	ds_read_b64_tr_b16 v[84:85], v94 offset:0xa00
	v_mfma_f32_32x32x16_bf16 v[0:15], v[70:73], v[86:89], v[0:15]
	ds_read_b64_tr_b16 v[86:87], v94 offset:0x1200
	ds_read_b64_tr_b16 v[88:89], v94 offset:0x1a00
	v_mfma_f32_32x32x16_bf16 v[0:15], v[74:77], v[90:93], v[0:15]
	ds_read_b64_tr_b16 v[90:91], v94 offset:0x2200
	ds_read_b64_tr_b16 v[92:93], v94 offset:0x2a00
	v_mfma_f32_32x32x16_bf16 v[0:15], v[78:81], v[100:103], v[0:15]
	ds_read_b64_tr_b16 v[100:101], v94 offset:0x3200
	ds_read_b64_tr_b16 v[102:103], v94 offset:0x3a00
	s_waitcnt lgkmcnt(0)
	v_mfma_f32_32x32x16_bf16 v[48:63], v[66:69], v[82:85], v[48:63]
	ds_read_b64_tr_b16 v[82:83], v94 offset:0x400
	ds_read_b64_tr_b16 v[84:85], v94 offset:0xc00
	v_mfma_f32_32x32x16_bf16 v[48:63], v[70:73], v[86:89], v[48:63]
	ds_read_b64_tr_b16 v[86:87], v94 offset:0x1400
	ds_read_b64_tr_b16 v[88:89], v94 offset:0x1c00
	v_mfma_f32_32x32x16_bf16 v[48:63], v[74:77], v[90:93], v[48:63]
	ds_read_b64_tr_b16 v[90:91], v94 offset:0x2400
	ds_read_b64_tr_b16 v[92:93], v94 offset:0x2c00
	v_mfma_f32_32x32x16_bf16 v[48:63], v[78:81], v[100:103], v[48:63]
	ds_read_b64_tr_b16 v[100:101], v94 offset:0x3400
	ds_read_b64_tr_b16 v[102:103], v94 offset:0x3c00
	s_waitcnt lgkmcnt(0)
; DEV int crow(int r, int hi) { return (r & 3) + 8 * (r >> 2) + 4 * hi; }
; DEV void attn_pass(const u16* __restrict__ Qb, const u16* __restrict__ Kh, const u16* __restrict__ Vh, int seq, f32x16* o, float* rli) {
;     ...
;   if (hi == 0) li_l[r32] = l_reg; asm volatile("s_waitcnt lgkmcnt(0)" ::: "memory");
; #pragma unroll
;   for (int r = 0; r < 16; ++r) rli[r] = __builtin_amdgcn_rcpf(li_l[crow(r, hi)]);
;   __syncthreads();
; DEV void attn_item(const Params& p, int l, int b, int h, int qb, int dry) {
;     ...
;     int lz = 0; asm volatile("" : "+v"(lz));
;     float* sp = scr + (wid * 64) * 64 + lane + lz;
; #pragma unroll
;     for (int d0 = 0; d0 < 4; ++d0)
; #pragma unroll
;       for (int r = 0; r < 16; ++r) sp[(d0 * 16 + r) * 64] = o[d0][r] * rli[r];
	v_mfma_f32_32x32x16_bf16 v[32:47], v[66:69], v[82:85], v[32:47]
	ds_read_b64_tr_b16 v[82:83], v94 offset:0x600
	ds_read_b64_tr_b16 v[84:85], v94 offset:0xe00
	v_mfma_f32_32x32x16_bf16 v[32:47], v[70:73], v[86:89], v[32:47]
	ds_read_b64_tr_b16 v[86:87], v94 offset:0x1600
	ds_read_b64_tr_b16 v[88:89], v94 offset:0x1e00
	v_mfma_f32_32x32x16_bf16 v[32:47], v[74:77], v[90:93], v[32:47]
	ds_read_b64_tr_b16 v[90:91], v94 offset:0x2600
	ds_read_b64_tr_b16 v[92:93], v94 offset:0x2e00
	v_mfma_f32_32x32x16_bf16 v[32:47], v[78:81], v[100:103], v[32:47]
	ds_read_b64_tr_b16 v[100:101], v94 offset:0x3600
	ds_read_b64_tr_b16 v[102:103], v94 offset:0x3e00
	s_waitcnt lgkmcnt(0)
	v_mfma_f32_32x32x16_bf16 v[16:31], v[66:69], v[82:85], v[16:31]
	v_mfma_f32_32x32x16_bf16 v[16:31], v[70:73], v[86:89], v[16:31]
	v_mfma_f32_32x32x16_bf16 v[16:31], v[74:77], v[90:93], v[16:31]
	v_mfma_f32_32x32x16_bf16 v[16:31], v[78:81], v[100:103], v[16:31]
	s_and_saveexec_b64 s[0:1], s[6:7]
	v_add_f32_e32 v66, v96, v97
	v_fmac_f32_e32 v66, v170, v141
	v_add_f32_e32 v64, v64, v65
	v_fmac_f32_e32 v64, v66, v98
	ds_write_b32 v169, v64
	s_or_b64 exec, exec, s[0:1]
	s_waitcnt lgkmcnt(0)
	v_add_u32_e32 v72, v168, v162
	ds_read_b128 v[64:67], v72
	ds_read_b128 v[68:71], v72 offset:32
	v_and_b32_e32 v73, 63, v172
	v_lshlrev_b32_e32 v162, 2, v73
	s_movk_i32 s8, 0x2000
	s_waitcnt lgkmcnt(1)
	v_rcp_f32_e32 v74, v64
	v_rcp_f32_e32 v75, v65
	v_rcp_f32_e32 v76, v66
	v_rcp_f32_e32 v77, v67
	ds_read_b128 v[64:67], v72 offset:64
	s_waitcnt lgkmcnt(1)
	v_rcp_f32_e32 v78, v68
	v_rcp_f32_e32 v79, v69
	v_rcp_f32_e32 v80, v70
	v_rcp_f32_e32 v81, v71
	ds_read_b128 v[68:71], v72 offset:96
	s_waitcnt lgkmcnt(1)
	v_rcp_f32_e32 v82, v65
	v_lshlrev_b32_e32 v65, 6, v172
	v_rcp_f32_e32 v83, v66
	v_and_b32_e32 v66, 0xfffff000, v65
	v_rcp_f32_e32 v84, v67
	v_ashrrev_i32_e32 v67, 31, v66
	v_rcp_f32_e32 v72, v64
	v_mov_b32_e32 v64, v163
	v_lshl_add_u64 v[66:67], v[66:67], 2, s[56:57]
	s_waitcnt lgkmcnt(0)
	s_barrier
	v_lshl_add_u64 v[154:155], v[66:67], 0, v[162:163]
	v_ashrrev_i32_e32 v65, 31, v64
	v_lshl_add_u64 v[64:65], v[64:65], 2, v[154:155]
	v_mul_f32_e32 v0, v0, v74
	global_store_dword v[64:65], v0, off
	v_mul_f32_e32 v0, v1, v75
	global_store_dword v[64:65], v0, off offset:256
	v_mul_f32_e32 v0, v2, v76
	global_store_dword v[64:65], v0, off offset:512
	v_mul_f32_e32 v0, v3, v77
	global_store_dword v[64:65], v0, off offset:768
	v_mul_f32_e32 v0, v4, v78
	global_store_dword v[64:65], v0, off offset:1024
	v_mul_f32_e32 v0, v5, v79
	global_store_dword v[64:65], v0, off offset:1280
	v_mul_f32_e32 v0, v6, v80
	global_store_dword v[64:65], v0, off offset:1536
	v_mul_f32_e32 v0, v7, v81
	v_rcp_f32_e32 v68, v68
	global_store_dword v[64:65], v0, off offset:1792
	v_mul_f32_e32 v0, v8, v72
	v_rcp_f32_e32 v69, v69
	global_store_dword v[64:65], v0, off offset:2048
	v_mul_f32_e32 v0, v9, v82
	v_rcp_f32_e32 v70, v70
	global_store_dword v[64:65], v0, off offset:2304
	v_mul_f32_e32 v0, v10, v83
	v_rcp_f32_e32 v71, v71
	global_store_dword v[64:65], v0, off offset:2560
	v_mul_f32_e32 v0, v11, v84
	global_store_dword v[64:65], v0, off offset:2816
	v_mul_f32_e32 v0, v12, v68
	global_store_dword v[64:65], v0, off offset:3072
	v_mul_f32_e32 v0, v13, v69
	global_store_dword v[64:65], v0, off offset:3328
	v_mul_f32_e32 v0, v14, v70
	global_store_dword v[64:65], v0, off offset:3584
	v_mul_f32_e32 v0, v15, v71
	global_store_dword v[64:65], v0, off offset:3840
	v_add_co_u32_e32 v0, vcc, s87, v64
	v_mul_f32_e32 v4, v48, v74
	s_nop 0
	v_addc_co_u32_e32 v1, vcc, 0, v65, vcc
	v_add_co_u32_e32 v2, vcc, s8, v64
	s_or_b32 s6, s47, 1
	s_nop 0
	v_addc_co_u32_e32 v3, vcc, 0, v65, vcc
	global_store_dword v[2:3], v4, off offset:-4096
	v_mul_f32_e32 v4, v49, v75
	global_store_dword v[0:1], v4, off offset:256
	v_mul_f32_e32 v4, v50, v76
	global_store_dword v[0:1], v4, off offset:512
	v_mul_f32_e32 v4, v51, v77
	global_store_dword v[0:1], v4, off offset:768
	v_mul_f32_e32 v4, v52, v78
	global_store_dword v[0:1], v4, off offset:1024
	v_mul_f32_e32 v4, v53, v79
	global_store_dword v[0:1], v4, off offset:1280
	v_mul_f32_e32 v4, v54, v80
	global_store_dword v[0:1], v4, off offset:1536
	v_mul_f32_e32 v4, v55, v81
	global_store_dword v[0:1], v4, off offset:1792
	v_mul_f32_e32 v4, v56, v72
	global_store_dword v[0:1], v4, off offset:2048
	v_mul_f32_e32 v4, v57, v82
	global_store_dword v[0:1], v4, off offset:2304
	v_mul_f32_e32 v4, v58, v83
	global_store_dword v[0:1], v4, off offset:2560
	v_mul_f32_e32 v4, v59, v84
	global_store_dword v[0:1], v4, off offset:2816
	v_mul_f32_e32 v4, v60, v68
	global_store_dword v[0:1], v4, off offset:3072
	v_mul_f32_e32 v4, v61, v69
	global_store_dword v[0:1], v4, off offset:3328
	v_mul_f32_e32 v4, v62, v70
	global_store_dword v[0:1], v4, off offset:3584
	v_mul_f32_e32 v4, v63, v71
	global_store_dword v[0:1], v4, off offset:3840
	v_mul_f32_e32 v0, v32, v74
	global_store_dword v[2:3], v0, off
	v_mul_f32_e32 v0, v33, v75
	global_store_dword v[2:3], v0, off offset:256
	v_mul_f32_e32 v0, v34, v76
	global_store_dword v[2:3], v0, off offset:512
	v_mul_f32_e32 v0, v35, v77
	global_store_dword v[2:3], v0, off offset:768
	v_mul_f32_e32 v0, v36, v78
	global_store_dword v[2:3], v0, off offset:1024
	v_mul_f32_e32 v0, v37, v79
	global_store_dword v[2:3], v0, off offset:1280
	v_mul_f32_e32 v0, v38, v80
	global_store_dword v[2:3], v0, off offset:1536
	v_mul_f32_e32 v0, v39, v81
	global_store_dword v[2:3], v0, off offset:1792
	v_mul_f32_e32 v0, v40, v72
	global_store_dword v[2:3], v0, off offset:2048
	v_mul_f32_e32 v0, v41, v82
	global_store_dword v[2:3], v0, off offset:2304
	v_mul_f32_e32 v0, v42, v83
	global_store_dword v[2:3], v0, off offset:2560
; DEV int v_st(int k, int c) { const int kk = (k & ~0xC) | ((k & 4) << 1) | ((k & 8) >> 1); return ((kk >> 3) * 4 + (c >> 5)) * 512 + ((kk & 7) * 32 + (c & 31)) * 2; }
; DEV int v_rd_base(int lane) { return ((lane & 3) << 3) | (((lane >> 2) & 3) << 6) | (((lane >> 4) & 1) << 5) | (((lane >> 5) & 1) << 8); }
; #define SLOAD(i, k0) do { sr_[i].vs0 = *reinterpret_cast<const bf16x8*>(&Vh[(size_t)((k0) + sr) * 128 + sc]); sr_[i].vs1 = *reinterpret_cast<const bf16x8*>(&Vh[(size_t)((k0) + 32 + sr) * 128 + sc]); \
;     sr_[i].ks0 = *reinterpret_cast<const bf16x8*>(&Kh[(size_t)((k0) + kr) * 64 + kc]); } while (0)
; #define SWRITE(b, i) do { *(bf16x8*)(V_lds + (b) * AT_SHM_V + vst0) = sr_[i].vs0; *(bf16x8*)(V_lds + (b) * AT_SHM_V + vst1) = sr_[i].vs1; \
;     *(bf16x8*)(K_lds + (b) * AT_SHM_K + kst) = sr_[i].ks0; } while (0)
; DEV void attn_pass(const u16* __restrict__ Qb, const u16* __restrict__ Kh, const u16* __restrict__ Vh, int seq, f32x16* o, float* rli) {
;     ...
;   const u16* Qw = Qb + (size_t)(wid * 32 + r32) * 64 + hi * 8;
; #pragma unroll
;   for (int d0 = 0; d0 < 4; ++d0) qr[d0] = *reinterpret_cast<const bf16x8*>(Qw + d0 * 16);
;   const int sr = tid >> 4, sc = (tid & 15) * 8, vst0 = v_st(sr, sc), vst1 = v_st(32 + sr, sc);
;   const int kr = tid >> 3, kc = (tid & 7) * 8, kst = KSWZ64(kr, kc * 2);
;   const int vb0 = (int)(uintptr_t)(__attribute__((address_space(3))) char*)V_lds + v_rd_base(lane);
;   struct { bf16x8 vs0, vs1, ks0; } sr_[2];
;     ...
;   f32x16 pA0, pA1, pB0, pB1; float mnA, mnB, alA, alB; bf16x8 pa0, pa1, pa2, pa3; const int NT = seq / 64;
;   constexpr int SE = 0, SO = 1;
;   SLOAD(SE, 0); SLOAD(SO, 64);
;   asm volatile("s_waitcnt vmcnt(3)" ::: "memory"); SWRITE(0, SE); __syncthreads();
; DEV void attn_item(const Params& p, int l, int b, int h, int qb, int dry) {
;     ...
;     for (int d0 = 0; d0 < 4; ++d0)
; #pragma unroll
;       for (int r = 0; r < 16; ++r) sp[(d0 * 16 + r) * 64] = o[d0][r] * rli[r];
;   }
;   {
;     const int s = b * 16 + h * 2 + 1;
;     attn_pass(AQ + ((size_t)s * UU + uq) * 64, AK + (size_t)s * UU * 64, Vh, seq, o, rli);
	v_mul_f32_e32 v0, v43, v84
	global_store_dword v[2:3], v0, off offset:2816
	v_mul_f32_e32 v0, v44, v68
	global_store_dword v[2:3], v0, off offset:3072
	v_mul_f32_e32 v0, v45, v69
	global_store_dword v[2:3], v0, off offset:3328
	v_mul_f32_e32 v0, v46, v70
	global_store_dword v[2:3], v0, off offset:3584
	v_mul_f32_e32 v0, v47, v71
	global_store_dword v[2:3], v0, off offset:3840
	v_add_co_u32_e32 v0, vcc, s80, v64
	v_mul_f32_e32 v2, v16, v74
	s_nop 0
	v_addc_co_u32_e32 v1, vcc, 0, v65, vcc
	global_store_dword v[0:1], v2, off
	v_mul_f32_e32 v2, v17, v75
	global_store_dword v[0:1], v2, off offset:256
	v_mul_f32_e32 v2, v18, v76
	global_store_dword v[0:1], v2, off offset:512
	v_mul_f32_e32 v2, v19, v77
	global_store_dword v[0:1], v2, off offset:768
	v_mul_f32_e32 v2, v20, v78
	global_store_dword v[0:1], v2, off offset:1024
	v_mul_f32_e32 v2, v21, v79
	global_store_dword v[0:1], v2, off offset:1280
	v_mul_f32_e32 v2, v22, v80
	global_store_dword v[0:1], v2, off offset:1536
	v_mul_f32_e32 v2, v23, v81
	global_store_dword v[0:1], v2, off offset:1792
	v_mul_f32_e32 v2, v24, v72
	global_store_dword v[0:1], v2, off offset:2048
	v_mul_f32_e32 v2, v25, v82
	global_store_dword v[0:1], v2, off offset:2304
	v_mul_f32_e32 v2, v26, v83
	global_store_dword v[0:1], v2, off offset:2560
	v_mul_f32_e32 v2, v27, v84
	global_store_dword v[0:1], v2, off offset:2816
	v_mul_f32_e32 v2, v28, v68
	global_store_dword v[0:1], v2, off offset:3072
	v_mul_f32_e32 v2, v29, v69
	global_store_dword v[0:1], v2, off offset:3328
	v_mul_f32_e32 v2, v30, v70
	s_mul_i32 s0, s6, 0x1100
	global_store_dword v[0:1], v2, off offset:3584
	v_mul_f32_e32 v2, v31, v71
	s_mul_hi_i32 s1, s6, 0x1100
	s_add_u32 s0, s0, s46
	v_mov_b32_e32 v70, v252
	global_store_dword v[0:1], v2, off offset:3840
	s_addc_u32 s1, s1, 0
	s_lshl_b64 s[0:1], s[0:1], 7
	v_ashrrev_i32_e32 v48, 4, v70
	v_lshlrev_b32_e32 v20, 3, v70
	v_ashrrev_i32_e32 v49, 31, v48
	s_add_u32 s0, s36, s0
	v_and_b32_e32 v2, 0x78, v20
	v_add_u32_e32 v12, 32, v48
	v_lshlrev_b64 v[50:51], 8, v[48:49]
	s_addc_u32 s1, s37, s1
	s_mul_hi_i32 s7, s6, 0x88000
	s_mul_i32 s6, s6, 0x88000
	v_ashrrev_i32_e32 v14, 3, v70
	v_lshl_add_u64 v[0:1], s[64:65], 0, v[50:51]
	v_lshlrev_b32_e32 v2, 1, v2
	v_mov_b32_e32 v3, v163
	v_ashrrev_i32_e32 v13, 31, v12
	s_add_u32 s6, s38, s6
	v_lshl_add_u64 v[66:67], v[0:1], 0, v[2:3]
	v_lshlrev_b64 v[0:1], 8, v[12:13]
	v_ashrrev_i32_e32 v15, 31, v14
	s_addc_u32 s7, s39, s7
	v_lshlrev_b32_e32 v71, 4, v70
	v_lshl_add_u64 v[0:1], s[64:65], 0, v[0:1]
	v_lshlrev_b64 v[52:53], 7, v[14:15]
	v_and_b32_e32 v16, 0x70, v71
	v_lshl_add_u64 v[4:5], v[0:1], 0, v[2:3]
	v_lshl_add_u64 v[8:9], s[6:7], 0, v[52:53]
	v_mov_b32_e32 v17, v163
	global_load_dwordx4 v[0:3], v[66:67], off
	s_nop 0
	global_load_dwordx4 v[4:7], v[4:5], off
	v_lshl_add_u64 v[68:69], v[8:9], 0, v[16:17]
	global_load_dwordx4 v[8:11], v[68:69], off
	v_ashrrev_i32_e32 v13, 1, v70
	v_bfi_b32 v18, s68, v13, v70
	v_ashrrev_i32_e32 v19, 31, v18
	v_lshlrev_b64 v[18:19], 7, v[18:19]
	v_lshrrev_b32_e32 v13, 1, v70
	v_lshl_add_u64 v[18:19], s[0:1], 0, v[18:19]
	v_and_b32_e32 v156, 16, v13
	v_mov_b32_e32 v157, v163
	v_lshl_add_u64 v[18:19], v[18:19], 0, v[156:157]
	global_load_dwordx4 v[108:111], v[18:19], off
	global_load_dwordx4 v[104:107], v[18:19], off offset:32
	global_load_dwordx4 v[100:103], v[18:19], off offset:64
	global_load_dwordx4 v[96:99], v[18:19], off offset:96
	v_and_b32_e32 v13, 0xfffff0, v48
	v_lshlrev_b32_e32 v15, 1, v48
	v_and_or_b32 v13, v15, 8, v13
	v_lshrrev_b32_e32 v13, 1, v13
	v_bfe_u32 v17, v20, 5, 2
	v_lshrrev_b32_e32 v15, 1, v48
	v_or_b32_e32 v13, v13, v17
	v_and_b32_e32 v73, 3, v48
	v_lshlrev_b32_e32 v72, 9, v13
	v_and_or_b32 v13, v15, 4, v73
	v_and_b32_e32 v15, 0xfffff0, v12
	v_lshlrev_b32_e32 v12, 1, v12
	v_and_or_b32 v12, v12, 8, v15
	v_lshrrev_b32_e32 v12, 1, v12
	v_or_b32_e32 v12, v12, v17
	v_lshlrev_b32_e32 v13, 6, v13
	v_and_b32_e32 v74, 48, v71
	v_lshlrev_b32_e32 v75, 9, v12
	v_or3_b32 v18, v72, v13, v74
	v_or3_b32 v17, v75, v13, v74
	v_lshlrev_b32_e32 v12, 7, v14
	v_and_b32_e32 v13, 0x70, v70
	v_bitop3_b32 v76, v16, v12, v13 bitop3:0xde
	v_add_co_u32_e32 v12, vcc, s75, v66
	s_movk_i32 s0, 0x6000
	s_nop 0
	v_addc_co_u32_e32 v13, vcc, 0, v67, vcc
	global_load_dwordx4 v[54:57], v[12:13], off
	v_add_co_u32_e32 v12, vcc, s0, v66
	v_and_b32_e32 v49, 31, v70
	s_nop 0
	v_addc_co_u32_e32 v13, vcc, 0, v67, vcc
	v_add_co_u32_e32 v14, vcc, s8, v68
	v_lshlrev_b32_e32 v80, 7, v49
	s_nop 0
	v_addc_co_u32_e32 v15, vcc, 0, v69, vcc
	global_load_dwordx4 v[58:61], v[12:13], off
	global_load_dwordx4 v[62:65], v[14:15], off
	v_and_b32_e32 v81, 0x70, v20
	v_add_u32_e32 v77, 0, v18
	v_add_u32_e32 v78, 0, v17
	v_bitop3_b32 v175, v156, v80, v81 bitop3:0xde
	s_waitcnt vmcnt(3)
	v_add_u32_e32 v79, 0, v76
	v_or_b32_e32 v83, 32, v156
	v_bitop3_b32 v178, v83, v80, v81 bitop3:0xde
	v_and_b32_e32 v82, 63, v70
	s_mov_b32 s0, 0xa000
	v_and_b32_e32 v180, 0xc0, v71
	v_or_b32_e32 v71, 64, v156
	v_bitop3_b32 v177, v71, v80, v81 bitop3:0xde
	v_or_b32_e32 v84, 0x60, v156
	v_bitop3_b32 v176, v84, v80, v81 bitop3:0xde
	s_mov_b32 s8, 0
	s_mov_b32 s9, s8
	s_mov_b32 s10, s8
	s_mov_b32 s11, s8
	s_mov_b32 s12, s8
	s_mov_b32 s13, s8
	s_mov_b32 s14, s8
	s_mov_b32 s15, s8
	s_mov_b32 s16, s8
	s_mov_b32 s17, s8
	s_waitcnt vmcnt(9)
	ds_write_b128 v77, v[0:3]
	s_waitcnt vmcnt(8)
	ds_write_b128 v78, v[4:7]
	v_add_u32_e32 v4, 0, v175
	v_and_b32_e32 v5, 0x3fffffc0, v70
	s_waitcnt vmcnt(7)
	ds_write_b128 v79, v[8:11] offset:49152
	s_waitcnt lgkmcnt(0)
	s_barrier
; #define SLOAD(i, k0) do { sr_[i].vs0 = *reinterpret_cast<const bf16x8*>(&Vh[(size_t)((k0) + sr) * 128 + sc]); sr_[i].vs1 = *reinterpret_cast<const bf16x8*>(&Vh[(size_t)((k0) + 32 + sr) * 128 + sc]); \
;     sr_[i].ks0 = *reinterpret_cast<const bf16x8*>(&Kh[(size_t)((k0) + kr) * 64 + kc]); } while (0)
; #define SWRITE(b, i) do { *(bf16x8*)(V_lds + (b) * AT_SHM_V + vst0) = sr_[i].vs0; *(bf16x8*)(V_lds + (b) * AT_SHM_V + vst1) = sr_[i].vs1; \
;     *(bf16x8*)(K_lds + (b) * AT_SHM_K + kst) = sr_[i].ks0; } while (0)
; #define SWAIT() asm volatile("s_waitcnt vmcnt(3)" ::: "memory")
; DEV void qkt(f32x16& p0, f32x16& p1, const char* Ks, const bf16x8* qr, int r32, int hi) {
;   p0 = f32x16{}; p1 = f32x16{};
; #pragma unroll
;   for (int d0 = 0; d0 < 4; ++d0) { int cb = (d0 * 16 + hi * 8) * 2;
;     bf16x8 b0 = *reinterpret_cast<const bf16x8*>(Ks + KSWZ64(r32, cb));
;     bf16x8 b1 = *reinterpret_cast<const bf16x8*>(Ks + KSWZ64(32 + r32, cb));
;     p0 = __builtin_amdgcn_mfma_f32_32x32x16_bf16(b0, qr[d0], p0, 0, 0, 0);
;     p1 = __builtin_amdgcn_mfma_f32_32x32x16_bf16(b1, qr[d0], p1, 0, 0, 0); }
; }
; DEV void attn_pass(const u16* __restrict__ Qb, const u16* __restrict__ Kh, const u16* __restrict__ Vh, int seq, f32x16* o, float* rli) {
;     ...
;   asm volatile("s_waitcnt vmcnt(3)" ::: "memory"); SWRITE(0, SE); __syncthreads();
;   if (2 < NT) SLOAD(SE, 2 * 64);
;   qkt(pA0, pA1, K_lds, qr, r32, hi); partialSM(pA0, pA1, m_reg, mnA, alA);
;   SWAIT(); SWRITE(1, SO); __syncthreads();
	ds_read_b128 v[0:3], v4 offset:49152
	v_lshl_add_u32 v157, v5, 2, s48
	ds_read_b128 v[4:7], v4 offset:53248
	v_add_u32_e32 v8, 0, v178
	s_waitcnt vmcnt(6) lgkmcnt(1)
	v_mfma_f32_32x32x16_bf16 v[16:31], v[0:3], v[108:111], 0
	ds_read_b128 v[0:3], v8 offset:49152
	s_mov_b32 s18, s8
	s_mov_b32 s19, s8
	s_mov_b32 s20, s8
	s_mov_b32 s21, s8
	s_mov_b32 s22, s8
	s_mov_b32 s23, s8
	s_waitcnt lgkmcnt(1)
	v_mfma_f32_32x32x16_bf16 v[32:47], v[4:7], v[108:111], 0
	v_lshlrev_b32_e32 v4, 3, v82
	v_lshlrev_b32_e32 v5, 1, v70
	v_and_b32_e32 v179, 24, v4
	v_and_b32_e32 v181, 32, v5
	v_and_b32_e32 v182, 0x100, v4
	ds_read_b128 v[4:7], v8 offset:53248
	v_add_co_u32_e32 v8, vcc, s75, v68
	s_waitcnt vmcnt(5) lgkmcnt(0)
	v_mfma_f32_32x32x16_bf16 v[32:47], v[4:7], v[104:107], v[32:47]
	v_addc_co_u32_e32 v9, vcc, 0, v69, vcc
	v_add_co_u32_e32 v10, vcc, s0, v66
	s_mov_b32 s0, 0x8000
	s_nop 0
	v_addc_co_u32_e32 v11, vcc, 0, v67, vcc
	v_add_co_u32_e32 v4, vcc, s0, v66
	v_add_u32_e32 v6, 0, v177
	s_nop 0
	v_addc_co_u32_e32 v5, vcc, 0, v67, vcc
	v_mfma_f32_32x32x16_bf16 v[16:31], v[0:3], v[104:107], v[16:31]
	ds_read_b128 v[0:3], v6 offset:49152
	global_load_dwordx4 v[120:123], v[8:9], off
	global_load_dwordx4 v[112:115], v[10:11], off
	global_load_dwordx4 v[116:119], v[4:5], off
	v_add_u32_e32 v8, 0, v176
	ds_read_b128 v[4:7], v6 offset:53248
	ds_read_b128 v[66:69], v8 offset:53248
	v_lshl_add_u32 v173, v49, 2, v157
	s_waitcnt vmcnt(7) lgkmcnt(2)
	v_mfma_f32_32x32x16_bf16 v[16:31], v[0:3], v[100:103], v[16:31]
	ds_read_b128 v[0:3], v8 offset:49152
	s_waitcnt vmcnt(3)
	s_waitcnt vmcnt(5)
	ds_write_b128 v77, v[54:57] offset:16384
	s_waitcnt vmcnt(4)
	ds_write_b128 v78, v[58:61] offset:16384
	s_waitcnt vmcnt(3)
	ds_write_b128 v79, v[62:65] offset:57344
	v_mov_b32_e32 v54, 0xf149f2ca
	s_mov_b32 s0, 0x10000
	s_mov_b32 s1, 0xe000
	s_mov_b32 s46, 2
	s_waitcnt lgkmcnt(5)
	v_mfma_f32_32x32x16_bf16 v[32:47], v[4:7], v[100:103], v[32:47]
	s_mov_b32 s47, 1
	s_mov_b32 s48, 4
	s_mov_b32 s64, 3
	v_cmp_gt_u32_e64 s[6:7], 32, v82
	v_add_u32_e32 v183, 0x10000, v76
	v_add_u32_e32 v184, 0, v80
	v_bitop3_b32 v198, v156, s0, v81 bitop3:0xde
	s_waitcnt lgkmcnt(3)
; #define SWRITE(b, i) do { *(bf16x8*)(V_lds + (b) * AT_SHM_V + vst0) = sr_[i].vs0; *(bf16x8*)(V_lds + (b) * AT_SHM_V + vst1) = sr_[i].vs1; \
;     *(bf16x8*)(K_lds + (b) * AT_SHM_K + kst) = sr_[i].ks0; } while (0)
; #define SWAIT() asm volatile("s_waitcnt vmcnt(3)" ::: "memory")
; DEV void partialSM(f32x16& p0, f32x16& p1, float& m_reg, float& mn, float& alpha) {
;   constexpr float C = AT_SCALE * 1.4426950408889634f;
;   float pmax = p0[0];
; #pragma unroll
;   for (int r = 1; r < 16; ++r) pmax = fmaxf(pmax, p0[r]);
; #pragma unroll
;   for (int r = 0; r < 16; ++r) pmax = fmaxf(pmax, p1[r]);
;   { auto rr = __builtin_amdgcn_permlane32_swap(__float_as_uint(pmax), __float_as_uint(pmax), false, false);
;     pmax = fmaxf(__uint_as_float(rr[0]), __uint_as_float(rr[1])); }
;   if (__builtin_expect(__all(pmax - m_reg <= AT_THR / AT_SCALE), 1)) { mn = m_reg; alpha = 1.f; }
;   else { mn = fmaxf(m_reg, pmax); alpha = __builtin_amdgcn_exp2f((m_reg - mn) * C); m_reg = mn; }
;   float mnC = -mn * C;
; #pragma unroll
;   for (int r = 0; r < 16; ++r) p0[r] = fmaf(p0[r], C, mnC);
; #pragma unroll
;   for (int r = 0; r < 16; ++r) p1[r] = fmaf(p1[r], C, mnC);
; #pragma unroll
;   for (int r = 0; r < 16; ++r) p0[r] = __builtin_amdgcn_exp2f(p0[r]);
; DEV void attn_pass(const u16* __restrict__ Qb, const u16* __restrict__ Kh, const u16* __restrict__ Vh, int seq, f32x16* o, float* rli) {
;     ...
;   qkt(pA0, pA1, K_lds, qr, r32, hi); partialSM(pA0, pA1, m_reg, mnA, alA);
;   SWAIT(); SWRITE(1, SO); __syncthreads();
	v_mfma_f32_32x32x16_bf16 v[16:31], v[0:3], v[96:99], v[16:31]
	v_mov_b64_e32 v[0:1], s[8:9]
	v_mov_b64_e32 v[2:3], s[10:11]
	v_mov_b64_e32 v[4:5], s[12:13]
	v_mov_b64_e32 v[6:7], s[14:15]
	v_mov_b64_e32 v[8:9], s[16:17]
	v_mov_b64_e32 v[10:11], s[18:19]
	v_mov_b64_e32 v[12:13], s[20:21]
	v_mfma_f32_32x32x16_bf16 v[32:47], v[66:69], v[96:99], v[32:47]
	s_nop 3
	v_max_f32_e32 v66, v17, v17
	v_max_f32_e32 v67, v16, v16
	v_max_f32_e32 v66, v67, v66
	v_max3_f32 v66, v66, v18, v19
	v_max3_f32 v66, v66, v20, v21
	v_max3_f32 v66, v66, v22, v23
	v_max3_f32 v66, v66, v24, v25
	v_max3_f32 v66, v66, v26, v27
	v_max3_f32 v66, v66, v28, v29
	v_max3_f32 v66, v66, v30, v31
	v_max3_f32 v66, v66, v32, v33
	v_max3_f32 v66, v66, v34, v35
	v_max3_f32 v66, v66, v36, v37
	v_max3_f32 v66, v66, v38, v39
	v_max3_f32 v66, v66, v40, v41
	v_max3_f32 v66, v66, v42, v43
	v_max3_f32 v66, v66, v44, v45
	v_max3_f32 v66, v66, v46, v47
	v_mov_b32_e32 v67, v66
	s_nop 1
	v_permlane32_swap_b32_e32 v66, v67
	v_max_f32_e32 v67, v67, v67
	v_max_f32_e32 v66, v66, v66
	v_max_f32_e32 v66, v66, v67
	v_mov_b64_e32 v[14:15], s[22:23]
	v_add_f32_e32 v67, 0x7149f2ca, v66
	s_mov_b32 s18, 0x4138aa3b
	v_cmp_ge_f32_e32 vcc, s18, v67
	s_cmp_eq_u64 vcc, exec
	v_max_f32_e32 v55, 0xf149f2ca, v66
	s_cselect_b64 vcc, -1, 0
	v_cndmask_b32_e32 v140, v55, v54, vcc
	v_mul_f32_e32 v54, 0xbf800000, v140
	v_mov_b32_e32 v236, v54
	v_mov_b32_e32 v237, v54
	v_mov_b32_e32 v238, v54
	v_mov_b32_e32 v239, v54
	v_mov_b32_e32 v240, v54
	v_mov_b32_e32 v241, v54
	v_mov_b32_e32 v242, v54
	v_mov_b32_e32 v243, v54
	v_mov_b32_e32 v244, v54
	v_mov_b32_e32 v245, v54
	v_mov_b32_e32 v246, v54
	v_mov_b32_e32 v247, v54
	v_mov_b32_e32 v248, v54
	v_mov_b32_e32 v249, v54
	v_mov_b32_e32 v250, v54
	v_mov_b32_e32 v251, v54
	v_fmamk_f32 v16, v16, 0x3f800000, v54
	v_exp_f32_e32 v150, v16
	v_fmamk_f32 v16, v17, 0x3f800000, v54
	v_exp_f32_e32 v170, v16
	v_fmamk_f32 v16, v18, 0x3f800000, v54
	v_exp_f32_e32 v151, v16
	v_fmamk_f32 v16, v19, 0x3f800000, v54
	v_exp_f32_e32 v171, v16
	v_fmamk_f32 v16, v20, 0x3f800000, v54
	v_exp_f32_e32 v168, v16
	v_fmamk_f32 v16, v21, 0x3f800000, v54
	v_exp_f32_e32 v217, v16
	v_fmamk_f32 v16, v22, 0x3f800000, v54
	v_exp_f32_e32 v169, v16
	v_fmamk_f32 v16, v23, 0x3f800000, v54
	v_exp_f32_e32 v218, v16
	v_fmamk_f32 v16, v24, 0x3f800000, v54
	v_exp_f32_e32 v142, v16
	v_fmamk_f32 v16, v25, 0x3f800000, v54
	v_exp_f32_e32 v146, v16
	v_fmamk_f32 v16, v26, 0x3f800000, v54
	v_exp_f32_e32 v143, v16
	v_fmamk_f32 v16, v27, 0x3f800000, v54
	v_exp_f32_e32 v147, v16
	v_fmamk_f32 v16, v28, 0x3f800000, v54
	v_exp_f32_e32 v144, v16
	v_fmamk_f32 v16, v29, 0x3f800000, v54
	v_exp_f32_e32 v148, v16
	v_fmamk_f32 v16, v30, 0x3f800000, v54
	v_exp_f32_e32 v145, v16
	v_add3_u32 v16, v182, 0, v180
	v_add3_u32 v199, v16, v181, v179
	v_lshlrev_b32_e32 v16, 5, v48
	v_pk_fma_f32 v[132:133], v[38:39], s[86:87], v[54:55] op_sel_hi:[1,0,0]
	v_sub_f32_e32 v38, 0xf149f2ca, v55
	v_and_b32_e32 v16, 0x100, v16
	v_lshlrev_b32_e32 v17, 6, v73
	v_and_b32_e32 v18, 7, v70
	v_mul_f32_e32 v38, 0x3f800000, v38
	v_or3_b32 v20, v75, v16, v17
	v_or3_b32 v21, v72, v16, v17
	v_lshl_add_u64 v[16:17], s[62:63], 0, v[52:53]
	v_lshlrev_b32_e32 v18, 4, v18
	v_mov_b32_e32 v19, v163
	v_exp_f32_e32 v38, v38
	v_lshl_add_u64 v[16:17], v[16:17], 0, v[18:19]
	v_and_b32_e32 v18, 15, v70
	v_pk_fma_f32 v[124:125], v[46:47], s[86:87], v[54:55] op_sel_hi:[1,0,0]
	v_pk_fma_f32 v[126:127], v[44:45], s[86:87], v[54:55] op_sel_hi:[1,0,0]
	v_pk_fma_f32 v[128:129], v[42:43], s[86:87], v[54:55] op_sel_hi:[1,0,0]
	v_pk_fma_f32 v[130:131], v[40:41], s[86:87], v[54:55] op_sel_hi:[1,0,0]
	v_pk_fma_f32 v[134:135], v[36:37], s[86:87], v[54:55] op_sel_hi:[1,0,0]
	v_pk_fma_f32 v[136:137], v[34:35], s[86:87], v[54:55] op_sel_hi:[1,0,0]
	v_pk_fma_f32 v[138:139], v[32:33], s[86:87], v[54:55] op_sel_hi:[1,0,0]
	v_fmac_f32_e32 v54, 0x3f800000, v31
	v_lshl_add_u64 v[158:159], s[96:97], 0, v[16:17]
	v_lshl_add_u64 v[16:17], s[52:53], 0, v[50:51]
	v_lshlrev_b32_e32 v18, 4, v18
	v_exp_f32_e32 v149, v54
	v_lshl_add_u64 v[16:17], v[16:17], 0, v[18:19]
	v_lshl_add_u64 v[160:161], s[96:97], 0, v[16:17]
	v_add3_u32 v16, v182, s49, v180
	v_cndmask_b32_e64 v185, v38, 1.0, vcc
	v_add_u32_e32 v206, 0x8000, v20
	v_add_u32_e32 v207, 0x8000, v21
	v_add_u32_e32 v209, 0xc000, v20
	v_add_u32_e32 v210, 0xc000, v21
	v_add3_u32 v211, v16, v181, v179
	v_mov_b64_e32 v[62:63], v[14:15]
	v_mov_b64_e32 v[46:47], v[14:15]
	v_mov_b64_e32 v[30:31], v[14:15]
	v_bitop3_b32 v200, v83, s0, v81 bitop3:0xde
	v_bitop3_b32 v201, v156, s1, v81 bitop3:0xde
	v_bitop3_b32 v202, v71, s0, v81 bitop3:0xde
	v_bitop3_b32 v203, v83, s1, v81 bitop3:0xde
	v_bitop3_b32 v204, v84, s0, v81 bitop3:0xde
	v_add_u32_e32 v205, 0, v74
	v_add_u32_e32 v208, 0x12000, v76
	v_bitop3_b32 v212, v71, s1, v81 bitop3:0xde
	v_bitop3_b32 v213, v84, s1, v81 bitop3:0xde
	v_mov_b32_e32 v174, 0
	v_mov_b64_e32 v[60:61], v[12:13]
	v_mov_b64_e32 v[58:59], v[10:11]
	v_mov_b64_e32 v[56:57], v[8:9]
	v_mov_b64_e32 v[54:55], v[6:7]
	v_mov_b64_e32 v[52:53], v[4:5]
	v_mov_b64_e32 v[50:51], v[2:3]
	v_mov_b64_e32 v[48:49], v[0:1]
	v_mov_b64_e32 v[44:45], v[12:13]
	v_mov_b64_e32 v[42:43], v[10:11]
	v_mov_b64_e32 v[40:41], v[8:9]
	v_mov_b64_e32 v[38:39], v[6:7]
	v_mov_b64_e32 v[36:37], v[4:5]
	v_mov_b64_e32 v[34:35], v[2:3]
	v_mov_b64_e32 v[32:33], v[0:1]
	v_mov_b64_e32 v[28:29], v[12:13]
	v_mov_b64_e32 v[26:27], v[10:11]
	v_mov_b64_e32 v[24:25], v[8:9]
	v_mov_b64_e32 v[22:23], v[6:7]
	v_mov_b64_e32 v[20:21], v[4:5]
	v_mov_b64_e32 v[18:19], v[2:3]
	v_mov_b64_e32 v[16:17], v[0:1]
	v_readfirstlane_b32 s0, v252
	s_nop 1
	s_cmp_lt_u32 s0, 0x100
	s_cbranch_scc1 .Lprio_b
	s_setprio 1

; #define SBAR() __builtin_amdgcn_sched_barrier(0)
; DEV void finishSM(f32x16& p0, f32x16& p1, float alpha, float& l_reg, bf16x8& pa0, bf16x8& pa1, bf16x8& pa2, bf16x8& pa3) {
; #pragma unroll
;   for (int r = 0; r < 16; ++r) p1[r] = __builtin_amdgcn_exp2f(p1[r]);
;   float ps = 0;
; #pragma unroll
;   for (int r = 0; r < 16; ++r) ps += p0[r];
; #pragma unroll
;   for (int r = 0; r < 16; ++r) ps += p1[r];
;   { auto rr = __builtin_amdgcn_permlane32_swap(__float_as_uint(ps), __float_as_uint(ps), false, false);
;     ps = __uint_as_float(rr[0]) + __uint_as_float(rr[1]); }
;   l_reg = l_reg * alpha + ps;
;     ...
;   PK4(p0, 0, pa0); PK4(p0, 8, pa1); PK4(p1, 0, pa2); PK4(p1, 8, pa3);
; DEV void attn_pass(const u16* __restrict__ Qb, const u16* __restrict__ Kh, const u16* __restrict__ Vh, int seq, f32x16* o, float* rli) {
;     ...
;   { const int bl = (NT - 1) % 3, bp = (NT - 2) % 3;
;     SBAR(); qkt(pB0, pB1, K_lds + bl * AT_SHM_K, qr, r32, hi);
;     finishSM(pA0, pA1, alA, l_reg, pa0, pa1, pa2, pa3); SBAR();
;     pv_d0(o, vb0 + bp * AT_SHM_V, pa0, pa1, pa2, pa3); partialSM(pB0, pB1, m_reg, mnB, alB);
.LBB0_102:
	s_setprio 0
	v_mov_b32_e32 v140, 0
	v_or_b32_e32 v64, v179, v180
	v_or3_b32 v64, v64, v181, v182
	v_add_u32_e32 v112, 0, v64
	v_add_u32_e32 v68, s45, v175
	ds_read_b128 v[64:67], v68 offset:49152
	ds_read_b128 v[68:71], v68 offset:53248
	v_add_u32_e32 v113, s45, v178
	v_exp_f32_e32 v118, v129
	v_exp_f32_e32 v119, v126
	s_waitcnt lgkmcnt(1)
	v_mfma_f32_32x32x16_bf16 v[80:95], v[64:67], v[108:111], v[236:251]
	v_exp_f32_e32 v120, v127
	v_exp_f32_e32 v121, v124
	v_exp_f32_e32 v122, v125
	s_waitcnt lgkmcnt(0)
	v_mfma_f32_32x32x16_bf16 v[64:79], v[68:71], v[108:111], v[236:251]
	ds_read_b128 v[108:111], v113 offset:49152
	ds_read_b128 v[114:117], v113 offset:53248
	v_exp_f32_e32 v113, v132
	s_waitcnt lgkmcnt(1)
	v_mfma_f32_32x32x16_bf16 v[80:95], v[108:111], v[104:107], v[80:95]
	v_add_u32_e32 v108, s45, v177
	s_waitcnt lgkmcnt(0)
	v_mfma_f32_32x32x16_bf16 v[64:79], v[114:117], v[104:107], v[64:79]
	ds_read_b128 v[104:107], v108 offset:49152
	ds_read_b128 v[108:111], v108 offset:53248
	v_exp_f32_e32 v114, v133
	v_exp_f32_e32 v115, v130
	v_exp_f32_e32 v116, v131
	v_exp_f32_e32 v117, v128
	s_waitcnt lgkmcnt(1)
	v_mfma_f32_32x32x16_bf16 v[80:95], v[104:107], v[100:103], v[80:95]
	v_add_u32_e32 v104, s45, v176
	s_waitcnt lgkmcnt(0)
	v_mfma_f32_32x32x16_bf16 v[64:79], v[108:111], v[100:103], v[64:79]
	ds_read_b128 v[100:103], v104 offset:49152
	ds_read_b128 v[104:107], v104 offset:53248
	v_exp_f32_e32 v108, v136
	v_exp_f32_e32 v109, v137
	v_exp_f32_e32 v110, v134
	v_exp_f32_e32 v111, v135
	s_waitcnt lgkmcnt(1)
	v_mfma_f32_32x32x16_bf16 v[80:95], v[100:103], v[96:99], v[80:95]
	v_cvt_pk_bf16_f32 v100, v168, v217
	v_cvt_pk_bf16_f32 v101, v169, v218
	v_cvt_pk_bf16_f32 v102, v142, v146
	v_cvt_pk_bf16_f32 v103, v143, v147
	s_waitcnt lgkmcnt(0)
	v_mfma_f32_32x32x16_bf16 v[64:79], v[104:107], v[96:99], v[64:79]
	v_add_f32_e32 v96, v170, v150
	v_add_f32_e32 v96, v151, v96
	v_add_f32_e32 v96, v171, v96
	v_add_f32_e32 v96, v168, v96
	v_add_f32_e32 v96, v217, v96
	v_add_f32_e32 v96, v169, v96
	v_add_f32_e32 v96, v218, v96
	v_add_f32_e32 v96, v142, v96
	v_add_f32_e32 v96, v146, v96
	v_add_f32_e32 v96, v143, v96
	v_add_f32_e32 v96, v147, v96
	v_exp_f32_e32 v106, v138
	v_add_f32_e32 v96, v144, v96
	v_exp_f32_e32 v107, v139
	v_add_f32_e32 v96, v148, v96
	v_add_f32_e32 v96, v145, v96
	v_add_f32_e32 v96, v149, v96
	v_add_f32_e32 v96, v106, v96
	v_add_f32_e32 v96, v107, v96
	v_add_f32_e32 v96, v108, v96
	v_add_f32_e32 v96, v109, v96
	v_add_f32_e32 v96, v110, v96
	v_add_f32_e32 v96, v111, v96
	v_add_f32_e32 v96, v113, v96
	v_add_f32_e32 v96, v114, v96
	v_add_f32_e32 v96, v115, v96
	v_add_f32_e32 v96, v116, v96
	v_add_f32_e32 v96, v117, v96
	v_add_f32_e32 v96, v118, v96
	v_add_f32_e32 v96, v119, v96
	v_add_f32_e32 v96, v120, v96
	v_add_f32_e32 v96, v121, v96
	v_add_f32_e32 v96, v122, v96
	v_mov_b32_e32 v97, v96
	v_cvt_pk_bf16_f32 v98, v150, v170
	v_cvt_pk_bf16_f32 v99, v151, v171
	s_nop 1
	v_permlane32_swap_b32_e32 v96, v97
	v_permlane32_swap_b32_e32 v98, v100
	v_permlane32_swap_b32_e32 v99, v101
	v_cvt_pk_bf16_f32 v104, v144, v148
	v_cvt_pk_bf16_f32 v105, v145, v149
	v_cvt_pk_bf16_f32 v106, v106, v107
	v_cvt_pk_bf16_f32 v107, v108, v109
	v_cvt_pk_bf16_f32 v108, v110, v111
	v_cvt_pk_bf16_f32 v109, v113, v114
	v_cvt_pk_bf16_f32 v114, v115, v116
	v_cvt_pk_bf16_f32 v115, v117, v118
	v_cvt_pk_bf16_f32 v116, v119, v120
	v_cvt_pk_bf16_f32 v117, v121, v122
	s_nop 0
	v_permlane32_swap_b32_e32 v102, v104
	v_permlane32_swap_b32_e32 v103, v105
	v_permlane32_swap_b32_e32 v106, v108
	v_permlane32_swap_b32_e32 v107, v109
	v_permlane32_swap_b32_e32 v114, v116
	v_permlane32_swap_b32_e32 v115, v117
	v_add_u32_e32 v110, s50, v112
	ds_read_b64_tr_b16 v[118:119], v110 offset:0
	ds_read_b64_tr_b16 v[120:121], v110 offset:0x800
	ds_read_b64_tr_b16 v[122:123], v110 offset:0x1000
	ds_read_b64_tr_b16 v[124:125], v110 offset:0x1800
	ds_read_b64_tr_b16 v[126:127], v110 offset:0x2000
	ds_read_b64_tr_b16 v[128:129], v110 offset:0x2800
	ds_read_b64_tr_b16 v[130:131], v110 offset:0x3000
	ds_read_b64_tr_b16 v[132:133], v110 offset:0x3800
	s_waitcnt lgkmcnt(0)
	s_nop 0
	v_mfma_f32_32x32x16_bf16 v[0:15], v[98:101], v[118:121], v[0:15]
	ds_read_b64_tr_b16 v[118:119], v110 offset:0x200
	ds_read_b64_tr_b16 v[120:121], v110 offset:0xa00
	v_mfma_f32_32x32x16_bf16 v[0:15], v[102:105], v[122:125], v[0:15]
	ds_read_b64_tr_b16 v[122:123], v110 offset:0x1200
	ds_read_b64_tr_b16 v[124:125], v110 offset:0x1a00
	v_mfma_f32_32x32x16_bf16 v[0:15], v[106:109], v[126:129], v[0:15]
	ds_read_b64_tr_b16 v[126:127], v110 offset:0x2200
	ds_read_b64_tr_b16 v[128:129], v110 offset:0x2a00
	v_mfma_f32_32x32x16_bf16 v[0:15], v[114:117], v[130:133], v[0:15]
	ds_read_b64_tr_b16 v[130:131], v110 offset:0x3200
	ds_read_b64_tr_b16 v[132:133], v110 offset:0x3a00
	s_waitcnt lgkmcnt(0)
; #define RESC(a) do { if (__any((a) < 1.f)) { if (hi == 0) al_l[r32] = (a); asm volatile("s_waitcnt lgkmcnt(0)" ::: "memory"); \
;     for (int d = 0; d < 4; ++d) for (int r = 0; r < 16; ++r) o[d][r] *= al_l[crow(r, hi)]; } } while (0)
; DEV void partialSM(f32x16& p0, f32x16& p1, float& m_reg, float& mn, float& alpha) {
;   constexpr float C = AT_SCALE * 1.4426950408889634f;
;   float pmax = p0[0];
; #pragma unroll
;   for (int r = 1; r < 16; ++r) pmax = fmaxf(pmax, p0[r]);
; #pragma unroll
;   for (int r = 0; r < 16; ++r) pmax = fmaxf(pmax, p1[r]);
;   { auto rr = __builtin_amdgcn_permlane32_swap(__float_as_uint(pmax), __float_as_uint(pmax), false, false);
;     pmax = fmaxf(__uint_as_float(rr[0]), __uint_as_float(rr[1])); }
;   if (__builtin_expect(__all(pmax - m_reg <= AT_THR / AT_SCALE), 1)) { mn = m_reg; alpha = 1.f; }
;   else { mn = fmaxf(m_reg, pmax); alpha = __builtin_amdgcn_exp2f((m_reg - mn) * C); m_reg = mn; }
; DEV void attn_pass(const u16* __restrict__ Qb, const u16* __restrict__ Kh, const u16* __restrict__ Vh, int seq, f32x16* o, float* rli) {
;     ...
;     pv_d0(o, vb0 + bp * AT_SHM_V, pa0, pa1, pa2, pa3); partialSM(pB0, pB1, m_reg, mnB, alB);
;     RESC(alB);
	v_mfma_f32_32x32x16_bf16 v[48:63], v[98:101], v[118:121], v[48:63]
	ds_read_b64_tr_b16 v[118:119], v110 offset:0x400
	ds_read_b64_tr_b16 v[120:121], v110 offset:0xc00
	v_mfma_f32_32x32x16_bf16 v[48:63], v[102:105], v[122:125], v[48:63]
	ds_read_b64_tr_b16 v[122:123], v110 offset:0x1400
	ds_read_b64_tr_b16 v[124:125], v110 offset:0x1c00
	v_mfma_f32_32x32x16_bf16 v[48:63], v[106:109], v[126:129], v[48:63]
	ds_read_b64_tr_b16 v[126:127], v110 offset:0x2400
	ds_read_b64_tr_b16 v[128:129], v110 offset:0x2c00
	v_mfma_f32_32x32x16_bf16 v[48:63], v[114:117], v[130:133], v[48:63]
	ds_read_b64_tr_b16 v[130:131], v110 offset:0x3400
	ds_read_b64_tr_b16 v[132:133], v110 offset:0x3c00
	s_waitcnt lgkmcnt(0)
	v_mfma_f32_32x32x16_bf16 v[32:47], v[98:101], v[118:121], v[32:47]
	ds_read_b64_tr_b16 v[118:119], v110 offset:0x600
	ds_read_b64_tr_b16 v[120:121], v110 offset:0xe00
	v_mfma_f32_32x32x16_bf16 v[32:47], v[102:105], v[122:125], v[32:47]
	ds_read_b64_tr_b16 v[122:123], v110 offset:0x1600
	ds_read_b64_tr_b16 v[124:125], v110 offset:0x1e00
	v_mfma_f32_32x32x16_bf16 v[32:47], v[106:109], v[126:129], v[32:47]
	ds_read_b64_tr_b16 v[126:127], v110 offset:0x2600
	ds_read_b64_tr_b16 v[128:129], v110 offset:0x2e00
	v_mfma_f32_32x32x16_bf16 v[32:47], v[114:117], v[130:133], v[32:47]
	ds_read_b64_tr_b16 v[130:131], v110 offset:0x3600
	ds_read_b64_tr_b16 v[132:133], v110 offset:0x3e00
	s_waitcnt lgkmcnt(0)
	v_mfma_f32_32x32x16_bf16 v[16:31], v[98:101], v[118:121], v[16:31]
	v_max_f32_e32 v98, v81, v81
	v_max_f32_e32 v99, v80, v80
	v_max_f32_e32 v98, v99, v98
	v_max3_f32 v98, v98, v82, v83
	v_max3_f32 v98, v98, v84, v85
	v_max3_f32 v98, v98, v86, v87
	v_max3_f32 v98, v98, v88, v89
	v_max3_f32 v98, v98, v90, v91
	v_max3_f32 v98, v98, v92, v93
	v_mfma_f32_32x32x16_bf16 v[16:31], v[102:105], v[122:125], v[16:31]
	v_max3_f32 v98, v98, v94, v95
	v_max3_f32 v98, v98, v64, v65
	v_max3_f32 v98, v98, v66, v67
	v_max3_f32 v98, v98, v68, v69
	v_max3_f32 v98, v98, v70, v71
	v_max3_f32 v98, v98, v72, v73
	v_max3_f32 v98, v98, v74, v75
	v_max3_f32 v98, v98, v76, v77
	v_mfma_f32_32x32x16_bf16 v[16:31], v[106:109], v[126:129], v[16:31]
	v_max3_f32 v98, v98, v78, v79
	v_mov_b32_e32 v99, v98
	s_nop 1
	v_permlane32_swap_b32_e32 v98, v99
	v_max_f32_e32 v99, v99, v99
	v_max_f32_e32 v98, v98, v98
	v_max_f32_e32 v98, v98, v99
	v_sub_f32_e32 v99, v98, v140
	v_cmp_ge_f32_e32 vcc, s18, v99
	v_max_f32_e32 v99, v140, v140
	v_max_f32_e32 v99, v99, v98
	v_mfma_f32_32x32x16_bf16 v[16:31], v[114:117], v[130:133], v[16:31]
	v_sub_f32_e32 v98, v140, v99
	v_mul_f32_e32 v98, 0x3f800000, v98
	v_exp_f32_e32 v98, v98
	s_cmp_eq_u64 vcc, exec
	s_cselect_b64 s[0:1], -1, 0
	v_cndmask_b32_e64 v98, v98, 1.0, s[0:1]
	v_cmp_gt_f32_e32 vcc, 1.0, v98
	s_cbranch_vccz .LBB0_106
	s_mov_b64 s[8:9], exec
	s_and_b64 s[10:11], s[8:9], s[6:7]
	s_movk_i32 s45, 0x2000
	v_mov_b32_e32 v175, v235
	v_mov_b32_e32 v176, 0xb9500d01
	v_mov_b32_e32 v178, 0x37d00d01
	v_mov_b32_e32 v177, 0x7f800000
	s_mov_b64 exec, s[10:11]
	ds_write_b32 v173, v98 offset:128
	s_or_b64 exec, exec, s[8:9]
	s_waitcnt lgkmcnt(0)
	v_add_u32_e32 v113, v157, v156
	ds_read_b128 v[100:103], v113 offset:224
	ds_read_b128 v[104:107], v113 offset:192
	ds_read_b128 v[108:111], v113 offset:160
	ds_read_b128 v[114:117], v113 offset:128
	s_waitcnt lgkmcnt(3)
	v_pk_mul_f32 v[12:13], v[12:13], v[100:101]
	s_waitcnt lgkmcnt(2)
	v_pk_mul_f32 v[8:9], v[8:9], v[104:105]
	s_waitcnt lgkmcnt(1)
	v_pk_mul_f32 v[4:5], v[4:5], v[108:109]
	v_pk_mul_f32 v[14:15], v[14:15], v[102:103]
	v_pk_mul_f32 v[10:11], v[10:11], v[106:107]
	v_pk_mul_f32 v[6:7], v[6:7], v[110:111]
	s_waitcnt lgkmcnt(0)
	v_pk_mul_f32 v[2:3], v[2:3], v[116:117]
	v_pk_mul_f32 v[0:1], v[0:1], v[114:115]
	v_pk_mul_f32 v[60:61], v[60:61], v[100:101]
	v_pk_mul_f32 v[56:57], v[56:57], v[104:105]
	v_pk_mul_f32 v[52:53], v[52:53], v[108:109]
	v_pk_mul_f32 v[62:63], v[62:63], v[102:103]
	v_pk_mul_f32 v[58:59], v[58:59], v[106:107]
	v_pk_mul_f32 v[54:55], v[54:55], v[110:111]
	v_pk_mul_f32 v[50:51], v[50:51], v[116:117]
	v_pk_mul_f32 v[48:49], v[48:49], v[114:115]
	v_pk_mul_f32 v[44:45], v[44:45], v[100:101]
	v_pk_mul_f32 v[40:41], v[40:41], v[104:105]
	v_pk_mul_f32 v[36:37], v[36:37], v[108:109]
	v_pk_mul_f32 v[46:47], v[46:47], v[102:103]
	v_pk_mul_f32 v[42:43], v[42:43], v[106:107]
	v_pk_mul_f32 v[38:39], v[38:39], v[110:111]
	v_pk_mul_f32 v[34:35], v[34:35], v[116:117]
	v_pk_mul_f32 v[32:33], v[32:33], v[114:115]
	v_pk_mul_f32 v[28:29], v[28:29], v[100:101]
	v_pk_mul_f32 v[24:25], v[24:25], v[104:105]
	v_pk_mul_f32 v[20:21], v[20:21], v[108:109]
	v_pk_mul_f32 v[30:31], v[30:31], v[102:103]
	v_pk_mul_f32 v[26:27], v[26:27], v[106:107]
	v_pk_mul_f32 v[22:23], v[22:23], v[110:111]
	v_pk_mul_f32 v[18:19], v[18:19], v[116:117]
	v_pk_mul_f32 v[16:17], v[16:17], v[114:115]
	s_branch .LBB0_107
